# pointwise GEMM epilogue (P4): each block's gate load issued ahead of the previous block's store, wait relaxed to vmcnt(1) (8 sites)
# speedup vs baseline: 1.0063x; 1.0063x over previous
; __device__ __forceinline__ unsigned cvt_pk_bf16(float lo, float hi) { unsigned r; asm volatile("v_cvt_pk_bf16_f32 %0, %1, %2" : "=v"(r) : "v"(lo), "v"(hi)); return r; }
; __device__ __forceinline__ float bflo(unsigned u) { return __uint_as_float(u << 16); }
; __device__ __forceinline__ float bfhi(unsigned u) { return __uint_as_float(u & 0xffff0000u); }
; __device__ __forceinline__ float silu_f(float v) { return v / (1.f + __expf(-v)); }
;     __device__ __forceinline__ void operator()(const pg8::f32x4 (&acc)[2][2][4][2], const pg8::Unit& u, int wr, int wc, int fr, int fq) const {
;         const int row0 = u.pm * 256 + wr * 64 + fr, col0 = u.pn * 256 + wc * 32 + 8 * fq;
; #pragma unroll
;         for (int ai = 0; ai < 2; ++ai)
; #pragma unroll
;             for (int m = 0; m < 4; ++m) { const size_t row = (size_t)(row0 + ai * 128 + m * 16);
; #pragma unroll
;                 for (int bj = 0; bj < 2; ++bj) { const pg8::f32x4 v0 = acc[ai][bj][m][0], v1 = acc[ai][bj][m][1];
;                     const u32x4 gz = *(const u32x4*)(Z + row * DIN + goff + col0 + bj * 128); u32x4 w;
;                     w.x = pg8::cvt_pk_bf16(v0[0] * silu_f(bflo(gz.x)), v0[1] * silu_f(bfhi(gz.x))); w.y = pg8::cvt_pk_bf16(v0[2] * silu_f(bflo(gz.y)), v0[3] * silu_f(bfhi(gz.y)));
;                     w.z = pg8::cvt_pk_bf16(v1[0] * silu_f(bflo(gz.z)), v1[1] * silu_f(bfhi(gz.z))); w.w = pg8::cvt_pk_bf16(v1[2] * silu_f(bflo(gz.w)), v1[3] * silu_f(bfhi(gz.w)));
;                     *(u32x4*)(O + row * DM + coff + col0 + bj * 128) = w; } }
.LBB0_555:
	v_readlane_b32 s12, v254, 0
	v_lshl_or_b32 v130, s50, 8, v170
	v_readlane_b32 s13, v254, 1
	v_lshl_add_u32 v160, s52, 8, v168
	v_ashrrev_i32_e32 v131, 31, v130
	v_mov_b64_e32 v[162:163], s[12:13]
	v_mad_i64_i32 v[132:133], s[12:13], v160, s75, v[162:163]
	v_lshlrev_b64 v[144:145], 1, v[130:131]
	v_lshl_add_u64 v[130:131], v[132:133], 0, v[144:145]
	s_mov_b64 s[26:27], 0x3000
	v_lshl_add_u64 v[166:167], v[130:131], 0, s[26:27]
	v_add_co_u32_e32 v130, vcc, 0x3000, v130
	v_ashrrev_i32_e32 v161, 31, v160
	s_nop 0
	v_addc_co_u32_e32 v131, vcc, 0, v131, vcc
	global_load_dwordx4 v[130:133], v[130:131], off
	v_lshlrev_b64 v[164:165], 12, v[160:161]
	s_mov_b64 s[50:51], -1
	s_waitcnt vmcnt(0)
	v_lshlrev_b32_e32 v161, 16, v130
	v_mul_f32_e32 v172, 0xbfb8aa3b, v161
	v_exp_f32_e32 v172, v172
	v_and_b32_e32 v130, 0xffff0000, v130
	v_add_f32_e32 v172, 1.0, v172
	v_div_scale_f32 v173, s[12:13], v172, v172, v161
	v_rcp_f32_e32 v174, v173
	s_nop 0
	v_fma_f32 v175, -v173, v174, 1.0
	v_fmac_f32_e32 v174, v175, v174
	v_div_scale_f32 v175, vcc, v161, v172, v161
	v_mul_f32_e32 v176, v175, v174
	v_fma_f32 v177, -v173, v176, v175
	v_fmac_f32_e32 v176, v177, v174
	v_fma_f32 v173, -v173, v176, v175
	v_div_fmas_f32 v173, v173, v174, v176
	v_div_fixup_f32 v161, v173, v172, v161
	v_mul_f32_e32 v126, v126, v161
	v_mul_f32_e32 v161, 0xbfb8aa3b, v130
	v_exp_f32_e32 v161, v161
	s_nop 0
	v_add_f32_e32 v161, 1.0, v161
	v_div_scale_f32 v172, s[12:13], v161, v161, v130
	v_rcp_f32_e32 v173, v172
	s_nop 0
	v_fma_f32 v174, -v172, v173, 1.0
	v_fmac_f32_e32 v173, v174, v173
	v_div_scale_f32 v174, vcc, v130, v161, v130
	v_mul_f32_e32 v175, v174, v173
	v_fma_f32 v176, -v172, v175, v174
	v_fmac_f32_e32 v175, v176, v173
	v_fma_f32 v172, -v172, v175, v174
	v_div_fmas_f32 v172, v172, v173, v175
	v_div_fixup_f32 v130, v172, v161, v130
	v_mul_f32_e32 v127, v127, v130
	v_cvt_pk_bf16_f32 v126, v126, v127
	v_lshlrev_b32_e32 v127, 16, v131
	v_mul_f32_e32 v130, 0xbfb8aa3b, v127
	v_exp_f32_e32 v130, v130
	s_nop 0
	v_add_f32_e32 v130, 1.0, v130
	v_div_scale_f32 v161, s[12:13], v130, v130, v127
	v_rcp_f32_e32 v172, v161
	s_nop 0
	v_fma_f32 v173, -v161, v172, 1.0
	v_fmac_f32_e32 v172, v173, v172
	v_div_scale_f32 v173, vcc, v127, v130, v127
	v_mul_f32_e32 v174, v173, v172
	v_fma_f32 v175, -v161, v174, v173
	v_fmac_f32_e32 v174, v175, v172
	v_fma_f32 v161, -v161, v174, v173
	v_div_fmas_f32 v161, v161, v172, v174
	v_div_fixup_f32 v127, v161, v130, v127
	v_mul_f32_e32 v127, v128, v127
	v_and_b32_e32 v128, 0xffff0000, v131
	v_mul_f32_e32 v130, 0xbfb8aa3b, v128
	v_exp_f32_e32 v130, v130
	s_nop 0
	v_add_f32_e32 v130, 1.0, v130
	v_div_scale_f32 v131, s[12:13], v130, v130, v128
	v_rcp_f32_e32 v161, v131
	s_nop 0
	v_fma_f32 v172, -v131, v161, 1.0
	v_fmac_f32_e32 v161, v172, v161
	v_div_scale_f32 v172, vcc, v128, v130, v128
	v_mul_f32_e32 v173, v172, v161
	v_fma_f32 v174, -v131, v173, v172
	v_fmac_f32_e32 v173, v174, v161
	v_fma_f32 v131, -v131, v173, v172
	v_div_fmas_f32 v131, v131, v161, v173
	v_div_fixup_f32 v128, v131, v130, v128
	v_mul_f32_e32 v128, v129, v128
	v_cvt_pk_bf16_f32 v127, v127, v128
	v_lshlrev_b32_e32 v128, 16, v132
	v_mul_f32_e32 v129, 0xbfb8aa3b, v128
	v_exp_f32_e32 v129, v129
	s_nop 0
	v_add_f32_e32 v129, 1.0, v129
	v_div_scale_f32 v130, s[12:13], v129, v129, v128
	v_rcp_f32_e32 v131, v130
	s_nop 0
	v_fma_f32 v161, -v130, v131, 1.0
	v_fmac_f32_e32 v131, v161, v131
	v_div_scale_f32 v161, vcc, v128, v129, v128
	v_mul_f32_e32 v172, v161, v131
	v_fma_f32 v173, -v130, v172, v161
	v_fmac_f32_e32 v172, v173, v131
	v_fma_f32 v130, -v130, v172, v161
	v_div_fmas_f32 v130, v130, v131, v172
	v_div_fixup_f32 v128, v130, v129, v128
	v_mul_f32_e32 v122, v122, v128
	v_and_b32_e32 v128, 0xffff0000, v132
	v_mul_f32_e32 v129, 0xbfb8aa3b, v128
	v_exp_f32_e32 v129, v129
	s_nop 0
	v_add_f32_e32 v129, 1.0, v129
	v_div_scale_f32 v130, s[12:13], v129, v129, v128
	v_rcp_f32_e32 v131, v130
	s_nop 0
	v_fma_f32 v132, -v130, v131, 1.0
	v_fmac_f32_e32 v131, v132, v131
	v_div_scale_f32 v132, vcc, v128, v129, v128
	v_mul_f32_e32 v161, v132, v131
	v_fma_f32 v172, -v130, v161, v132
	v_fmac_f32_e32 v161, v172, v131
	v_fma_f32 v130, -v130, v161, v132
	v_div_fmas_f32 v130, v130, v131, v161
	v_div_fixup_f32 v128, v130, v129, v128
	v_mul_f32_e32 v123, v123, v128
	v_cvt_pk_bf16_f32 v128, v122, v123
	v_lshlrev_b32_e32 v122, 16, v133
	v_mul_f32_e32 v123, 0xbfb8aa3b, v122
	v_exp_f32_e32 v123, v123
	s_nop 0
	v_add_f32_e32 v123, 1.0, v123
	v_div_scale_f32 v129, s[12:13], v123, v123, v122
	v_rcp_f32_e32 v130, v129
	s_nop 0
	v_fma_f32 v131, -v129, v130, 1.0
	v_fmac_f32_e32 v130, v131, v130
	v_div_scale_f32 v131, vcc, v122, v123, v122
	v_mul_f32_e32 v132, v131, v130
	v_fma_f32 v161, -v129, v132, v131
	v_fmac_f32_e32 v132, v161, v130
	v_fma_f32 v129, -v129, v132, v131
	v_div_fmas_f32 v129, v129, v130, v132
	v_div_fixup_f32 v122, v129, v123, v122
	v_and_b32_e32 v123, 0xffff0000, v133
	v_mul_f32_e32 v122, v124, v122
	v_mul_f32_e32 v124, 0xbfb8aa3b, v123
	v_exp_f32_e32 v124, v124
	s_nop 0
	v_add_f32_e32 v124, 1.0, v124
	v_div_scale_f32 v129, s[12:13], v124, v124, v123
	v_rcp_f32_e32 v130, v129
	s_nop 0
	v_fma_f32 v131, -v129, v130, 1.0
	v_fmac_f32_e32 v130, v131, v130
	v_div_scale_f32 v131, vcc, v123, v124, v123
	v_mul_f32_e32 v132, v131, v130
	v_fma_f32 v133, -v129, v132, v131
	v_fmac_f32_e32 v132, v133, v130
	v_fma_f32 v129, -v129, v132, v131
	v_div_fmas_f32 v129, v129, v130, v132
	v_div_fixup_f32 v123, v129, v124, v123
	v_mul_f32_e32 v123, v125, v123
	v_cvt_pk_bf16_f32 v129, v122, v123
	v_lshl_add_u64 v[122:123], s[72:73], 0, v[164:165]
	v_lshl_add_u64 v[130:131], v[122:123], 0, v[144:145]
	global_load_dwordx4 v[122:125], v[166:167], off offset:256
	global_store_dwordx4 v[130:131], v[126:129], off
	s_waitcnt vmcnt(1)
; __device__ __forceinline__ unsigned cvt_pk_bf16(float lo, float hi) { unsigned r; asm volatile("v_cvt_pk_bf16_f32 %0, %1, %2" : "=v"(r) : "v"(lo), "v"(hi)); return r; }
; __device__ __forceinline__ float bflo(unsigned u) { return __uint_as_float(u << 16); }
; __device__ __forceinline__ float bfhi(unsigned u) { return __uint_as_float(u & 0xffff0000u); }
; __device__ __forceinline__ float silu_f(float v) { return v / (1.f + __expf(-v)); }
;     __device__ __forceinline__ void operator()(const pg8::f32x4 (&acc)[2][2][4][2], const pg8::Unit& u, int wr, int wc, int fr, int fq) const {
;     ...
;             for (int m = 0; m < 4; ++m) { const size_t row = (size_t)(row0 + ai * 128 + m * 16);
; #pragma unroll
;                 for (int bj = 0; bj < 2; ++bj) { const pg8::f32x4 v0 = acc[ai][bj][m][0], v1 = acc[ai][bj][m][1];
;                     const u32x4 gz = *(const u32x4*)(Z + row * DIN + goff + col0 + bj * 128); u32x4 w;
;                     w.x = pg8::cvt_pk_bf16(v0[0] * silu_f(bflo(gz.x)), v0[1] * silu_f(bfhi(gz.x))); w.y = pg8::cvt_pk_bf16(v0[2] * silu_f(bflo(gz.y)), v0[3] * silu_f(bfhi(gz.y)));
;                     w.z = pg8::cvt_pk_bf16(v1[0] * silu_f(bflo(gz.z)), v1[1] * silu_f(bfhi(gz.z))); w.w = pg8::cvt_pk_bf16(v1[2] * silu_f(bflo(gz.w)), v1[3] * silu_f(bfhi(gz.w)));
;                     *(u32x4*)(O + row * DM + coff + col0 + bj * 128) = w; } }
	v_lshlrev_b32_e32 v126, 16, v122
	v_mul_f32_e32 v127, 0xbfb8aa3b, v126
	v_exp_f32_e32 v127, v127
	v_and_b32_e32 v122, 0xffff0000, v122
	v_add_f32_e32 v127, 1.0, v127
	v_div_scale_f32 v128, s[12:13], v127, v127, v126
	v_rcp_f32_e32 v129, v128
	s_nop 0
	v_fma_f32 v132, -v128, v129, 1.0
	v_fmac_f32_e32 v129, v132, v129
	v_div_scale_f32 v132, vcc, v126, v127, v126
	v_mul_f32_e32 v133, v132, v129
	v_fma_f32 v161, -v128, v133, v132
	v_fmac_f32_e32 v133, v161, v129
	v_fma_f32 v128, -v128, v133, v132
	v_div_fmas_f32 v128, v128, v129, v133
	v_div_fixup_f32 v126, v128, v127, v126
	v_mul_f32_e32 v118, v118, v126
	v_mul_f32_e32 v126, 0xbfb8aa3b, v122
	v_exp_f32_e32 v126, v126
	s_nop 0
	v_add_f32_e32 v126, 1.0, v126
	v_div_scale_f32 v127, s[12:13], v126, v126, v122
	v_rcp_f32_e32 v128, v127
	s_nop 0
	v_fma_f32 v129, -v127, v128, 1.0
	v_fmac_f32_e32 v128, v129, v128
	v_div_scale_f32 v129, vcc, v122, v126, v122
	v_mul_f32_e32 v132, v129, v128
	v_fma_f32 v133, -v127, v132, v129
	v_fmac_f32_e32 v132, v133, v128
	v_fma_f32 v127, -v127, v132, v129
	v_div_fmas_f32 v127, v127, v128, v132
	v_div_fixup_f32 v122, v127, v126, v122
	v_mul_f32_e32 v119, v119, v122
	v_cvt_pk_bf16_f32 v118, v118, v119
	v_lshlrev_b32_e32 v119, 16, v123
	v_mul_f32_e32 v122, 0xbfb8aa3b, v119
	v_exp_f32_e32 v122, v122
	s_nop 0
	v_add_f32_e32 v122, 1.0, v122
	v_div_scale_f32 v126, s[12:13], v122, v122, v119
	v_rcp_f32_e32 v127, v126
	s_nop 0
	v_fma_f32 v128, -v126, v127, 1.0
	v_fmac_f32_e32 v127, v128, v127
	v_div_scale_f32 v128, vcc, v119, v122, v119
	v_mul_f32_e32 v129, v128, v127
	v_fma_f32 v132, -v126, v129, v128
	v_fmac_f32_e32 v129, v132, v127
	v_fma_f32 v126, -v126, v129, v128
	v_div_fmas_f32 v126, v126, v127, v129
	v_div_fixup_f32 v119, v126, v122, v119
	v_mul_f32_e32 v119, v120, v119
	v_and_b32_e32 v120, 0xffff0000, v123
	v_mul_f32_e32 v122, 0xbfb8aa3b, v120
	v_exp_f32_e32 v122, v122
	s_nop 0
	v_add_f32_e32 v122, 1.0, v122
	v_div_scale_f32 v123, s[12:13], v122, v122, v120
	v_rcp_f32_e32 v126, v123
	s_nop 0
	v_fma_f32 v127, -v123, v126, 1.0
	v_fmac_f32_e32 v126, v127, v126
	v_div_scale_f32 v127, vcc, v120, v122, v120
	v_mul_f32_e32 v128, v127, v126
	v_fma_f32 v129, -v123, v128, v127
	v_fmac_f32_e32 v128, v129, v126
	v_fma_f32 v123, -v123, v128, v127
	v_div_fmas_f32 v123, v123, v126, v128
	v_div_fixup_f32 v120, v123, v122, v120
	v_mul_f32_e32 v120, v121, v120
	v_cvt_pk_bf16_f32 v119, v119, v120
	v_lshlrev_b32_e32 v120, 16, v124
	v_mul_f32_e32 v121, 0xbfb8aa3b, v120
	v_exp_f32_e32 v121, v121
	s_nop 0
	v_add_f32_e32 v121, 1.0, v121
	v_div_scale_f32 v122, s[12:13], v121, v121, v120
	v_rcp_f32_e32 v123, v122
	s_nop 0
	v_fma_f32 v126, -v122, v123, 1.0
	v_fmac_f32_e32 v123, v126, v123
	v_div_scale_f32 v126, vcc, v120, v121, v120
	v_mul_f32_e32 v127, v126, v123
	v_fma_f32 v128, -v122, v127, v126
	v_fmac_f32_e32 v127, v128, v123
	v_fma_f32 v122, -v122, v127, v126
	v_div_fmas_f32 v122, v122, v123, v127
	v_div_fixup_f32 v120, v122, v121, v120
	v_mul_f32_e32 v114, v114, v120
	v_and_b32_e32 v120, 0xffff0000, v124
	v_mul_f32_e32 v121, 0xbfb8aa3b, v120
	v_exp_f32_e32 v121, v121
	s_nop 0
	v_add_f32_e32 v121, 1.0, v121
	v_div_scale_f32 v122, s[12:13], v121, v121, v120
	v_rcp_f32_e32 v123, v122
	s_nop 0
	v_fma_f32 v124, -v122, v123, 1.0
	v_fmac_f32_e32 v123, v124, v123
	v_div_scale_f32 v124, vcc, v120, v121, v120
	v_mul_f32_e32 v126, v124, v123
	v_fma_f32 v127, -v122, v126, v124
	v_fmac_f32_e32 v126, v127, v123
	v_fma_f32 v122, -v122, v126, v124
	v_div_fmas_f32 v122, v122, v123, v126
	v_div_fixup_f32 v120, v122, v121, v120
	v_mul_f32_e32 v115, v115, v120
	v_cvt_pk_bf16_f32 v120, v114, v115
	v_lshlrev_b32_e32 v114, 16, v125
	v_mul_f32_e32 v115, 0xbfb8aa3b, v114
	v_exp_f32_e32 v115, v115
	s_nop 0
	v_add_f32_e32 v115, 1.0, v115
	v_div_scale_f32 v121, s[12:13], v115, v115, v114
	v_rcp_f32_e32 v122, v121
	s_nop 0
	v_fma_f32 v123, -v121, v122, 1.0
	v_fmac_f32_e32 v122, v123, v122
	v_div_scale_f32 v123, vcc, v114, v115, v114
	v_mul_f32_e32 v124, v123, v122
	v_fma_f32 v126, -v121, v124, v123
	v_fmac_f32_e32 v124, v126, v122
	v_fma_f32 v121, -v121, v124, v123
	v_div_fmas_f32 v121, v121, v122, v124
	v_div_fixup_f32 v114, v121, v115, v114
	v_and_b32_e32 v115, 0xffff0000, v125
	v_mul_f32_e32 v114, v116, v114
	v_mul_f32_e32 v116, 0xbfb8aa3b, v115
	v_exp_f32_e32 v116, v116
	s_nop 0
	v_add_f32_e32 v116, 1.0, v116
	v_div_scale_f32 v121, s[12:13], v116, v116, v115
	v_rcp_f32_e32 v122, v121
	s_nop 0
	v_fma_f32 v123, -v121, v122, 1.0
	v_fmac_f32_e32 v122, v123, v122
	v_div_scale_f32 v123, vcc, v115, v116, v115
	v_mul_f32_e32 v124, v123, v122
	v_fma_f32 v125, -v121, v124, v123
	v_fmac_f32_e32 v124, v125, v122
	v_fma_f32 v121, -v121, v124, v123
	v_div_fmas_f32 v121, v121, v122, v124
	v_div_fixup_f32 v115, v121, v116, v115
	v_mul_f32_e32 v115, v117, v115
	v_cvt_pk_bf16_f32 v121, v114, v115
	v_or_b32_e32 v114, 16, v160
	v_ashrrev_i32_e32 v115, 31, v114
	global_store_dwordx4 v[130:131], v[118:121], off offset:256
	s_nop 1
	v_lshlrev_b64 v[118:119], 12, v[114:115]
	v_mad_i64_i32 v[114:115], s[12:13], v114, s75, v[162:163]
	v_lshl_add_u64 v[114:115], v[114:115], 0, v[144:145]
	v_lshl_add_u64 v[120:121], v[114:115], 0, s[26:27]
	v_add_co_u32_e32 v114, vcc, s5, v114
	s_nop 1
	v_addc_co_u32_e32 v115, vcc, 0, v115, vcc
	global_load_dwordx4 v[114:117], v[114:115], off
	s_waitcnt vmcnt(0)
; __device__ __forceinline__ unsigned cvt_pk_bf16(float lo, float hi) { unsigned r; asm volatile("v_cvt_pk_bf16_f32 %0, %1, %2" : "=v"(r) : "v"(lo), "v"(hi)); return r; }
; __device__ __forceinline__ float bflo(unsigned u) { return __uint_as_float(u << 16); }
; __device__ __forceinline__ float bfhi(unsigned u) { return __uint_as_float(u & 0xffff0000u); }
; __device__ __forceinline__ float silu_f(float v) { return v / (1.f + __expf(-v)); }
;     __device__ __forceinline__ void operator()(const pg8::f32x4 (&acc)[2][2][4][2], const pg8::Unit& u, int wr, int wc, int fr, int fq) const {
;     ...
;             for (int m = 0; m < 4; ++m) { const size_t row = (size_t)(row0 + ai * 128 + m * 16);
; #pragma unroll
;                 for (int bj = 0; bj < 2; ++bj) { const pg8::f32x4 v0 = acc[ai][bj][m][0], v1 = acc[ai][bj][m][1];
;                     const u32x4 gz = *(const u32x4*)(Z + row * DIN + goff + col0 + bj * 128); u32x4 w;
;                     w.x = pg8::cvt_pk_bf16(v0[0] * silu_f(bflo(gz.x)), v0[1] * silu_f(bfhi(gz.x))); w.y = pg8::cvt_pk_bf16(v0[2] * silu_f(bflo(gz.y)), v0[3] * silu_f(bfhi(gz.y)));
;                     w.z = pg8::cvt_pk_bf16(v1[0] * silu_f(bflo(gz.z)), v1[1] * silu_f(bfhi(gz.z))); w.w = pg8::cvt_pk_bf16(v1[2] * silu_f(bflo(gz.w)), v1[3] * silu_f(bfhi(gz.w)));
;                     *(u32x4*)(O + row * DM + coff + col0 + bj * 128) = w; } }
	v_lshlrev_b32_e32 v122, 16, v114
	v_mul_f32_e32 v123, 0xbfb8aa3b, v122
	v_exp_f32_e32 v123, v123
	v_and_b32_e32 v114, 0xffff0000, v114
	v_add_f32_e32 v123, 1.0, v123
	v_div_scale_f32 v124, s[12:13], v123, v123, v122
	v_rcp_f32_e32 v125, v124
	s_nop 0
	v_fma_f32 v126, -v124, v125, 1.0
	v_fmac_f32_e32 v125, v126, v125
	v_div_scale_f32 v126, vcc, v122, v123, v122
	v_mul_f32_e32 v127, v126, v125
	v_fma_f32 v128, -v124, v127, v126
	v_fmac_f32_e32 v127, v128, v125
	v_fma_f32 v124, -v124, v127, v126
	v_div_fmas_f32 v124, v124, v125, v127
	v_div_fixup_f32 v122, v124, v123, v122
	v_mul_f32_e32 v110, v110, v122
	v_mul_f32_e32 v122, 0xbfb8aa3b, v114
	v_exp_f32_e32 v122, v122
	s_nop 0
	v_add_f32_e32 v122, 1.0, v122
	v_div_scale_f32 v123, s[12:13], v122, v122, v114
	v_rcp_f32_e32 v124, v123
	s_nop 0
	v_fma_f32 v125, -v123, v124, 1.0
	v_fmac_f32_e32 v124, v125, v124
	v_div_scale_f32 v125, vcc, v114, v122, v114
	v_mul_f32_e32 v126, v125, v124
	v_fma_f32 v127, -v123, v126, v125
	v_fmac_f32_e32 v126, v127, v124
	v_fma_f32 v123, -v123, v126, v125
	v_div_fmas_f32 v123, v123, v124, v126
	v_div_fixup_f32 v114, v123, v122, v114
	v_mul_f32_e32 v111, v111, v114
	v_cvt_pk_bf16_f32 v110, v110, v111
	v_lshlrev_b32_e32 v111, 16, v115
	v_mul_f32_e32 v114, 0xbfb8aa3b, v111
	v_exp_f32_e32 v114, v114
	s_nop 0
	v_add_f32_e32 v114, 1.0, v114
	v_div_scale_f32 v122, s[12:13], v114, v114, v111
	v_rcp_f32_e32 v123, v122
	s_nop 0
	v_fma_f32 v124, -v122, v123, 1.0
	v_fmac_f32_e32 v123, v124, v123
	v_div_scale_f32 v124, vcc, v111, v114, v111
	v_mul_f32_e32 v125, v124, v123
	v_fma_f32 v126, -v122, v125, v124
	v_fmac_f32_e32 v125, v126, v123
	v_fma_f32 v122, -v122, v125, v124
	v_div_fmas_f32 v122, v122, v123, v125
	v_div_fixup_f32 v111, v122, v114, v111
	v_mul_f32_e32 v111, v112, v111
	v_and_b32_e32 v112, 0xffff0000, v115
	v_mul_f32_e32 v114, 0xbfb8aa3b, v112
	v_exp_f32_e32 v114, v114
	s_nop 0
	v_add_f32_e32 v114, 1.0, v114
	v_div_scale_f32 v115, s[12:13], v114, v114, v112
	v_rcp_f32_e32 v122, v115
	s_nop 0
	v_fma_f32 v123, -v115, v122, 1.0
	v_fmac_f32_e32 v122, v123, v122
	v_div_scale_f32 v123, vcc, v112, v114, v112
	v_mul_f32_e32 v124, v123, v122
	v_fma_f32 v125, -v115, v124, v123
	v_fmac_f32_e32 v124, v125, v122
	v_fma_f32 v115, -v115, v124, v123
	v_div_fmas_f32 v115, v115, v122, v124
	v_div_fixup_f32 v112, v115, v114, v112
	v_mul_f32_e32 v112, v113, v112
	v_cvt_pk_bf16_f32 v111, v111, v112
	v_lshlrev_b32_e32 v112, 16, v116
	v_mul_f32_e32 v113, 0xbfb8aa3b, v112
	v_exp_f32_e32 v113, v113
	s_nop 0
	v_add_f32_e32 v113, 1.0, v113
	v_div_scale_f32 v114, s[12:13], v113, v113, v112
	v_rcp_f32_e32 v115, v114
	s_nop 0
	v_fma_f32 v122, -v114, v115, 1.0
	v_fmac_f32_e32 v115, v122, v115
	v_div_scale_f32 v122, vcc, v112, v113, v112
	v_mul_f32_e32 v123, v122, v115
	v_fma_f32 v124, -v114, v123, v122
	v_fmac_f32_e32 v123, v124, v115
	v_fma_f32 v114, -v114, v123, v122
	v_div_fmas_f32 v114, v114, v115, v123
	v_div_fixup_f32 v112, v114, v113, v112
	v_mul_f32_e32 v106, v106, v112
	v_and_b32_e32 v112, 0xffff0000, v116
	v_mul_f32_e32 v113, 0xbfb8aa3b, v112
	v_exp_f32_e32 v113, v113
	s_nop 0
	v_add_f32_e32 v113, 1.0, v113
	v_div_scale_f32 v114, s[12:13], v113, v113, v112
	v_rcp_f32_e32 v115, v114
	s_nop 0
	v_fma_f32 v116, -v114, v115, 1.0
	v_fmac_f32_e32 v115, v116, v115
	v_div_scale_f32 v116, vcc, v112, v113, v112
	v_mul_f32_e32 v122, v116, v115
	v_fma_f32 v123, -v114, v122, v116
	v_fmac_f32_e32 v122, v123, v115
	v_fma_f32 v114, -v114, v122, v116
	v_div_fmas_f32 v114, v114, v115, v122
	v_div_fixup_f32 v112, v114, v113, v112
	v_mul_f32_e32 v107, v107, v112
	v_cvt_pk_bf16_f32 v112, v106, v107
	v_lshlrev_b32_e32 v106, 16, v117
	v_mul_f32_e32 v107, 0xbfb8aa3b, v106
	v_exp_f32_e32 v107, v107
	s_nop 0
	v_add_f32_e32 v107, 1.0, v107
	v_div_scale_f32 v113, s[12:13], v107, v107, v106
	v_rcp_f32_e32 v114, v113
	s_nop 0
	v_fma_f32 v115, -v113, v114, 1.0
	v_fmac_f32_e32 v114, v115, v114
	v_div_scale_f32 v115, vcc, v106, v107, v106
	v_mul_f32_e32 v116, v115, v114
	v_fma_f32 v122, -v113, v116, v115
	v_fmac_f32_e32 v116, v122, v114
	v_fma_f32 v113, -v113, v116, v115
	v_div_fmas_f32 v113, v113, v114, v116
	v_div_fixup_f32 v106, v113, v107, v106
	v_and_b32_e32 v107, 0xffff0000, v117
	v_mul_f32_e32 v106, v108, v106
	v_mul_f32_e32 v108, 0xbfb8aa3b, v107
	v_exp_f32_e32 v108, v108
	s_nop 0
	v_add_f32_e32 v108, 1.0, v108
	v_div_scale_f32 v113, s[12:13], v108, v108, v107
	v_rcp_f32_e32 v114, v113
	s_nop 0
	v_fma_f32 v115, -v113, v114, 1.0
	v_fmac_f32_e32 v114, v115, v114
	v_div_scale_f32 v115, vcc, v107, v108, v107
	v_mul_f32_e32 v116, v115, v114
	v_fma_f32 v117, -v113, v116, v115
	v_fmac_f32_e32 v116, v117, v114
	v_fma_f32 v113, -v113, v116, v115
	v_div_fmas_f32 v113, v113, v114, v116
	v_div_fixup_f32 v107, v113, v108, v107
	v_mul_f32_e32 v107, v109, v107
	v_cvt_pk_bf16_f32 v113, v106, v107
	v_lshl_add_u64 v[106:107], s[72:73], 0, v[118:119]
	v_lshl_add_u64 v[114:115], v[106:107], 0, v[144:145]
	global_load_dwordx4 v[106:109], v[120:121], off offset:256
	global_store_dwordx4 v[114:115], v[110:113], off
	s_waitcnt vmcnt(1)
; __device__ __forceinline__ unsigned cvt_pk_bf16(float lo, float hi) { unsigned r; asm volatile("v_cvt_pk_bf16_f32 %0, %1, %2" : "=v"(r) : "v"(lo), "v"(hi)); return r; }
; __device__ __forceinline__ float bflo(unsigned u) { return __uint_as_float(u << 16); }
; __device__ __forceinline__ float bfhi(unsigned u) { return __uint_as_float(u & 0xffff0000u); }
; __device__ __forceinline__ float silu_f(float v) { return v / (1.f + __expf(-v)); }
;     __device__ __forceinline__ void operator()(const pg8::f32x4 (&acc)[2][2][4][2], const pg8::Unit& u, int wr, int wc, int fr, int fq) const {
;     ...
;             for (int m = 0; m < 4; ++m) { const size_t row = (size_t)(row0 + ai * 128 + m * 16);
; #pragma unroll
;                 for (int bj = 0; bj < 2; ++bj) { const pg8::f32x4 v0 = acc[ai][bj][m][0], v1 = acc[ai][bj][m][1];
;                     const u32x4 gz = *(const u32x4*)(Z + row * DIN + goff + col0 + bj * 128); u32x4 w;
;                     w.x = pg8::cvt_pk_bf16(v0[0] * silu_f(bflo(gz.x)), v0[1] * silu_f(bfhi(gz.x))); w.y = pg8::cvt_pk_bf16(v0[2] * silu_f(bflo(gz.y)), v0[3] * silu_f(bfhi(gz.y)));
;                     w.z = pg8::cvt_pk_bf16(v1[0] * silu_f(bflo(gz.z)), v1[1] * silu_f(bfhi(gz.z))); w.w = pg8::cvt_pk_bf16(v1[2] * silu_f(bflo(gz.w)), v1[3] * silu_f(bfhi(gz.w)));
;                     *(u32x4*)(O + row * DM + coff + col0 + bj * 128) = w; } }
	v_lshlrev_b32_e32 v110, 16, v106
	v_mul_f32_e32 v111, 0xbfb8aa3b, v110
	v_exp_f32_e32 v111, v111
	v_and_b32_e32 v106, 0xffff0000, v106
	v_add_f32_e32 v111, 1.0, v111
	v_div_scale_f32 v112, s[12:13], v111, v111, v110
	v_rcp_f32_e32 v113, v112
	s_nop 0
	v_fma_f32 v116, -v112, v113, 1.0
	v_fmac_f32_e32 v113, v116, v113
	v_div_scale_f32 v116, vcc, v110, v111, v110
	v_mul_f32_e32 v117, v116, v113
	v_fma_f32 v118, -v112, v117, v116
	v_fmac_f32_e32 v117, v118, v113
	v_fma_f32 v112, -v112, v117, v116
	v_div_fmas_f32 v112, v112, v113, v117
	v_div_fixup_f32 v110, v112, v111, v110
	v_mul_f32_e32 v102, v102, v110
	v_mul_f32_e32 v110, 0xbfb8aa3b, v106
	v_exp_f32_e32 v110, v110
	s_nop 0
	v_add_f32_e32 v110, 1.0, v110
	v_div_scale_f32 v111, s[12:13], v110, v110, v106
	v_rcp_f32_e32 v112, v111
	s_nop 0
	v_fma_f32 v113, -v111, v112, 1.0
	v_fmac_f32_e32 v112, v113, v112
	v_div_scale_f32 v113, vcc, v106, v110, v106
	v_mul_f32_e32 v116, v113, v112
	v_fma_f32 v117, -v111, v116, v113
	v_fmac_f32_e32 v116, v117, v112
	v_fma_f32 v111, -v111, v116, v113
	v_div_fmas_f32 v111, v111, v112, v116
	v_div_fixup_f32 v106, v111, v110, v106
	v_mul_f32_e32 v103, v103, v106
	v_cvt_pk_bf16_f32 v102, v102, v103
	v_lshlrev_b32_e32 v103, 16, v107
	v_mul_f32_e32 v106, 0xbfb8aa3b, v103
	v_exp_f32_e32 v106, v106
	s_nop 0
	v_add_f32_e32 v106, 1.0, v106
	v_div_scale_f32 v110, s[12:13], v106, v106, v103
	v_rcp_f32_e32 v111, v110
	s_nop 0
	v_fma_f32 v112, -v110, v111, 1.0
	v_fmac_f32_e32 v111, v112, v111
	v_div_scale_f32 v112, vcc, v103, v106, v103
	v_mul_f32_e32 v113, v112, v111
	v_fma_f32 v116, -v110, v113, v112
	v_fmac_f32_e32 v113, v116, v111
	v_fma_f32 v110, -v110, v113, v112
	v_div_fmas_f32 v110, v110, v111, v113
	v_div_fixup_f32 v103, v110, v106, v103
	v_mul_f32_e32 v103, v104, v103
	v_and_b32_e32 v104, 0xffff0000, v107
	v_mul_f32_e32 v106, 0xbfb8aa3b, v104
	v_exp_f32_e32 v106, v106
	s_nop 0
	v_add_f32_e32 v106, 1.0, v106
	v_div_scale_f32 v107, s[12:13], v106, v106, v104
	v_rcp_f32_e32 v110, v107
	s_nop 0
	v_fma_f32 v111, -v107, v110, 1.0
	v_fmac_f32_e32 v110, v111, v110
	v_div_scale_f32 v111, vcc, v104, v106, v104
	v_mul_f32_e32 v112, v111, v110
	v_fma_f32 v113, -v107, v112, v111
	v_fmac_f32_e32 v112, v113, v110
	v_fma_f32 v107, -v107, v112, v111
	v_div_fmas_f32 v107, v107, v110, v112
	v_div_fixup_f32 v104, v107, v106, v104
	v_mul_f32_e32 v104, v105, v104
	v_cvt_pk_bf16_f32 v103, v103, v104
	v_lshlrev_b32_e32 v104, 16, v108
	v_mul_f32_e32 v105, 0xbfb8aa3b, v104
	v_exp_f32_e32 v105, v105
	s_nop 0
	v_add_f32_e32 v105, 1.0, v105
	v_div_scale_f32 v106, s[12:13], v105, v105, v104
	v_rcp_f32_e32 v107, v106
	s_nop 0
	v_fma_f32 v110, -v106, v107, 1.0
	v_fmac_f32_e32 v107, v110, v107
	v_div_scale_f32 v110, vcc, v104, v105, v104
	v_mul_f32_e32 v111, v110, v107
	v_fma_f32 v112, -v106, v111, v110
	v_fmac_f32_e32 v111, v112, v107
	v_fma_f32 v106, -v106, v111, v110
	v_div_fmas_f32 v106, v106, v107, v111
	v_div_fixup_f32 v104, v106, v105, v104
	v_mul_f32_e32 v98, v98, v104
	v_and_b32_e32 v104, 0xffff0000, v108
	v_mul_f32_e32 v105, 0xbfb8aa3b, v104
	v_exp_f32_e32 v105, v105
	s_nop 0
	v_add_f32_e32 v105, 1.0, v105
	v_div_scale_f32 v106, s[12:13], v105, v105, v104
	v_rcp_f32_e32 v107, v106
	s_nop 0
	v_fma_f32 v108, -v106, v107, 1.0
	v_fmac_f32_e32 v107, v108, v107
	v_div_scale_f32 v108, vcc, v104, v105, v104
	v_mul_f32_e32 v110, v108, v107
	v_fma_f32 v111, -v106, v110, v108
	v_fmac_f32_e32 v110, v111, v107
	v_fma_f32 v106, -v106, v110, v108
	v_div_fmas_f32 v106, v106, v107, v110
	v_div_fixup_f32 v104, v106, v105, v104
	v_mul_f32_e32 v99, v99, v104
	v_cvt_pk_bf16_f32 v104, v98, v99
	v_lshlrev_b32_e32 v98, 16, v109
	v_mul_f32_e32 v99, 0xbfb8aa3b, v98
	v_exp_f32_e32 v99, v99
	s_nop 0
	v_add_f32_e32 v99, 1.0, v99
	v_div_scale_f32 v105, s[12:13], v99, v99, v98
	v_rcp_f32_e32 v106, v105
	s_nop 0
	v_fma_f32 v107, -v105, v106, 1.0
	v_fmac_f32_e32 v106, v107, v106
	v_div_scale_f32 v107, vcc, v98, v99, v98
	v_mul_f32_e32 v108, v107, v106
	v_fma_f32 v110, -v105, v108, v107
	v_fmac_f32_e32 v108, v110, v106
	v_fma_f32 v105, -v105, v108, v107
	v_div_fmas_f32 v105, v105, v106, v108
	v_div_fixup_f32 v98, v105, v99, v98
	v_and_b32_e32 v99, 0xffff0000, v109
	v_mul_f32_e32 v98, v100, v98
	v_mul_f32_e32 v100, 0xbfb8aa3b, v99
	v_exp_f32_e32 v100, v100
	s_nop 0
	v_add_f32_e32 v100, 1.0, v100
	v_div_scale_f32 v105, s[12:13], v100, v100, v99
	v_rcp_f32_e32 v106, v105
	s_nop 0
	v_fma_f32 v107, -v105, v106, 1.0
	v_fmac_f32_e32 v106, v107, v106
	v_div_scale_f32 v107, vcc, v99, v100, v99
	v_mul_f32_e32 v108, v107, v106
	v_fma_f32 v109, -v105, v108, v107
	v_fmac_f32_e32 v108, v109, v106
	v_fma_f32 v105, -v105, v108, v107
	v_div_fmas_f32 v105, v105, v106, v108
	v_div_fixup_f32 v99, v105, v100, v99
	v_mul_f32_e32 v99, v101, v99
	v_cvt_pk_bf16_f32 v105, v98, v99
	v_or_b32_e32 v98, 32, v160
	v_ashrrev_i32_e32 v99, 31, v98
	global_store_dwordx4 v[114:115], v[102:105], off offset:256
	s_nop 1
	v_lshlrev_b64 v[102:103], 12, v[98:99]
	v_mad_i64_i32 v[98:99], s[12:13], v98, s75, v[162:163]
	v_lshl_add_u64 v[98:99], v[98:99], 0, v[144:145]
	v_lshl_add_u64 v[104:105], v[98:99], 0, s[26:27]
	v_add_co_u32_e32 v98, vcc, s5, v98
	s_nop 1
	v_addc_co_u32_e32 v99, vcc, 0, v99, vcc
	global_load_dwordx4 v[98:101], v[98:99], off
	s_waitcnt vmcnt(0)
; __device__ __forceinline__ unsigned cvt_pk_bf16(float lo, float hi) { unsigned r; asm volatile("v_cvt_pk_bf16_f32 %0, %1, %2" : "=v"(r) : "v"(lo), "v"(hi)); return r; }
; __device__ __forceinline__ float bflo(unsigned u) { return __uint_as_float(u << 16); }
; __device__ __forceinline__ float bfhi(unsigned u) { return __uint_as_float(u & 0xffff0000u); }
; __device__ __forceinline__ float silu_f(float v) { return v / (1.f + __expf(-v)); }
;     __device__ __forceinline__ void operator()(const pg8::f32x4 (&acc)[2][2][4][2], const pg8::Unit& u, int wr, int wc, int fr, int fq) const {
;     ...
;             for (int m = 0; m < 4; ++m) { const size_t row = (size_t)(row0 + ai * 128 + m * 16);
; #pragma unroll
;                 for (int bj = 0; bj < 2; ++bj) { const pg8::f32x4 v0 = acc[ai][bj][m][0], v1 = acc[ai][bj][m][1];
;                     const u32x4 gz = *(const u32x4*)(Z + row * DIN + goff + col0 + bj * 128); u32x4 w;
;                     w.x = pg8::cvt_pk_bf16(v0[0] * silu_f(bflo(gz.x)), v0[1] * silu_f(bfhi(gz.x))); w.y = pg8::cvt_pk_bf16(v0[2] * silu_f(bflo(gz.y)), v0[3] * silu_f(bfhi(gz.y)));
;                     w.z = pg8::cvt_pk_bf16(v1[0] * silu_f(bflo(gz.z)), v1[1] * silu_f(bfhi(gz.z))); w.w = pg8::cvt_pk_bf16(v1[2] * silu_f(bflo(gz.w)), v1[3] * silu_f(bfhi(gz.w)));
;                     *(u32x4*)(O + row * DM + coff + col0 + bj * 128) = w; } }
	v_lshlrev_b32_e32 v106, 16, v98
	v_mul_f32_e32 v107, 0xbfb8aa3b, v106
	v_exp_f32_e32 v107, v107
	v_and_b32_e32 v98, 0xffff0000, v98
	v_add_f32_e32 v107, 1.0, v107
	v_div_scale_f32 v108, s[12:13], v107, v107, v106
	v_rcp_f32_e32 v109, v108
	s_nop 0
	v_fma_f32 v110, -v108, v109, 1.0
	v_fmac_f32_e32 v109, v110, v109
	v_div_scale_f32 v110, vcc, v106, v107, v106
	v_mul_f32_e32 v111, v110, v109
	v_fma_f32 v112, -v108, v111, v110
	v_fmac_f32_e32 v111, v112, v109
	v_fma_f32 v108, -v108, v111, v110
	v_div_fmas_f32 v108, v108, v109, v111
	v_div_fixup_f32 v106, v108, v107, v106
	v_mul_f32_e32 v94, v94, v106
	v_mul_f32_e32 v106, 0xbfb8aa3b, v98
	v_exp_f32_e32 v106, v106
	s_nop 0
	v_add_f32_e32 v106, 1.0, v106
	v_div_scale_f32 v107, s[12:13], v106, v106, v98
	v_rcp_f32_e32 v108, v107
	s_nop 0
	v_fma_f32 v109, -v107, v108, 1.0
	v_fmac_f32_e32 v108, v109, v108
	v_div_scale_f32 v109, vcc, v98, v106, v98
	v_mul_f32_e32 v110, v109, v108
	v_fma_f32 v111, -v107, v110, v109
	v_fmac_f32_e32 v110, v111, v108
	v_fma_f32 v107, -v107, v110, v109
	v_div_fmas_f32 v107, v107, v108, v110
	v_div_fixup_f32 v98, v107, v106, v98
	v_mul_f32_e32 v95, v95, v98
	v_cvt_pk_bf16_f32 v94, v94, v95
	v_lshlrev_b32_e32 v95, 16, v99
	v_mul_f32_e32 v98, 0xbfb8aa3b, v95
	v_exp_f32_e32 v98, v98
	s_nop 0
	v_add_f32_e32 v98, 1.0, v98
	v_div_scale_f32 v106, s[12:13], v98, v98, v95
	v_rcp_f32_e32 v107, v106
	s_nop 0
	v_fma_f32 v108, -v106, v107, 1.0
	v_fmac_f32_e32 v107, v108, v107
	v_div_scale_f32 v108, vcc, v95, v98, v95
	v_mul_f32_e32 v109, v108, v107
	v_fma_f32 v110, -v106, v109, v108
	v_fmac_f32_e32 v109, v110, v107
	v_fma_f32 v106, -v106, v109, v108
	v_div_fmas_f32 v106, v106, v107, v109
	v_div_fixup_f32 v95, v106, v98, v95
	v_mul_f32_e32 v95, v96, v95
	v_and_b32_e32 v96, 0xffff0000, v99
	v_mul_f32_e32 v98, 0xbfb8aa3b, v96
	v_exp_f32_e32 v98, v98
	s_nop 0
	v_add_f32_e32 v98, 1.0, v98
	v_div_scale_f32 v99, s[12:13], v98, v98, v96
	v_rcp_f32_e32 v106, v99
	s_nop 0
	v_fma_f32 v107, -v99, v106, 1.0
	v_fmac_f32_e32 v106, v107, v106
	v_div_scale_f32 v107, vcc, v96, v98, v96
	v_mul_f32_e32 v108, v107, v106
	v_fma_f32 v109, -v99, v108, v107
	v_fmac_f32_e32 v108, v109, v106
	v_fma_f32 v99, -v99, v108, v107
	v_div_fmas_f32 v99, v99, v106, v108
	v_div_fixup_f32 v96, v99, v98, v96
	v_mul_f32_e32 v96, v97, v96
	v_cvt_pk_bf16_f32 v95, v95, v96
	v_lshlrev_b32_e32 v96, 16, v100
	v_mul_f32_e32 v97, 0xbfb8aa3b, v96
	v_exp_f32_e32 v97, v97
	s_nop 0
	v_add_f32_e32 v97, 1.0, v97
	v_div_scale_f32 v98, s[12:13], v97, v97, v96
	v_rcp_f32_e32 v99, v98
	s_nop 0
	v_fma_f32 v106, -v98, v99, 1.0
	v_fmac_f32_e32 v99, v106, v99
	v_div_scale_f32 v106, vcc, v96, v97, v96
	v_mul_f32_e32 v107, v106, v99
	v_fma_f32 v108, -v98, v107, v106
	v_fmac_f32_e32 v107, v108, v99
	v_fma_f32 v98, -v98, v107, v106
	v_div_fmas_f32 v98, v98, v99, v107
	v_div_fixup_f32 v96, v98, v97, v96
	v_mul_f32_e32 v90, v90, v96
	v_and_b32_e32 v96, 0xffff0000, v100
	v_mul_f32_e32 v97, 0xbfb8aa3b, v96
	v_exp_f32_e32 v97, v97
	s_nop 0
	v_add_f32_e32 v97, 1.0, v97
	v_div_scale_f32 v98, s[12:13], v97, v97, v96
	v_rcp_f32_e32 v99, v98
	s_nop 0
	v_fma_f32 v100, -v98, v99, 1.0
	v_fmac_f32_e32 v99, v100, v99
	v_div_scale_f32 v100, vcc, v96, v97, v96
	v_mul_f32_e32 v106, v100, v99
	v_fma_f32 v107, -v98, v106, v100
	v_fmac_f32_e32 v106, v107, v99
	v_fma_f32 v98, -v98, v106, v100
	v_div_fmas_f32 v98, v98, v99, v106
	v_div_fixup_f32 v96, v98, v97, v96
	v_mul_f32_e32 v91, v91, v96
	v_cvt_pk_bf16_f32 v96, v90, v91
	v_lshlrev_b32_e32 v90, 16, v101
	v_mul_f32_e32 v91, 0xbfb8aa3b, v90
	v_exp_f32_e32 v91, v91
	s_nop 0
	v_add_f32_e32 v91, 1.0, v91
	v_div_scale_f32 v97, s[12:13], v91, v91, v90
	v_rcp_f32_e32 v98, v97
	s_nop 0
	v_fma_f32 v99, -v97, v98, 1.0
	v_fmac_f32_e32 v98, v99, v98
	v_div_scale_f32 v99, vcc, v90, v91, v90
	v_mul_f32_e32 v100, v99, v98
	v_fma_f32 v106, -v97, v100, v99
	v_fmac_f32_e32 v100, v106, v98
	v_fma_f32 v97, -v97, v100, v99
	v_div_fmas_f32 v97, v97, v98, v100
	v_div_fixup_f32 v90, v97, v91, v90
	v_and_b32_e32 v91, 0xffff0000, v101
	v_mul_f32_e32 v90, v92, v90
	v_mul_f32_e32 v92, 0xbfb8aa3b, v91
	v_exp_f32_e32 v92, v92
	s_nop 0
	v_add_f32_e32 v92, 1.0, v92
	v_div_scale_f32 v97, s[12:13], v92, v92, v91
	v_rcp_f32_e32 v98, v97
	s_nop 0
	v_fma_f32 v99, -v97, v98, 1.0
	v_fmac_f32_e32 v98, v99, v98
	v_div_scale_f32 v99, vcc, v91, v92, v91
	v_mul_f32_e32 v100, v99, v98
	v_fma_f32 v101, -v97, v100, v99
	v_fmac_f32_e32 v100, v101, v98
	v_fma_f32 v97, -v97, v100, v99
	v_div_fmas_f32 v97, v97, v98, v100
	v_div_fixup_f32 v91, v97, v92, v91
	v_mul_f32_e32 v91, v93, v91
	v_cvt_pk_bf16_f32 v97, v90, v91
	v_lshl_add_u64 v[90:91], s[72:73], 0, v[102:103]
	v_lshl_add_u64 v[98:99], v[90:91], 0, v[144:145]
	global_load_dwordx4 v[90:93], v[104:105], off offset:256
	global_store_dwordx4 v[98:99], v[94:97], off
	s_waitcnt vmcnt(1)
; __device__ __forceinline__ unsigned cvt_pk_bf16(float lo, float hi) { unsigned r; asm volatile("v_cvt_pk_bf16_f32 %0, %1, %2" : "=v"(r) : "v"(lo), "v"(hi)); return r; }
; __device__ __forceinline__ float bflo(unsigned u) { return __uint_as_float(u << 16); }
; __device__ __forceinline__ float bfhi(unsigned u) { return __uint_as_float(u & 0xffff0000u); }
; __device__ __forceinline__ float silu_f(float v) { return v / (1.f + __expf(-v)); }
;     __device__ __forceinline__ void operator()(const pg8::f32x4 (&acc)[2][2][4][2], const pg8::Unit& u, int wr, int wc, int fr, int fq) const {
;     ...
;             for (int m = 0; m < 4; ++m) { const size_t row = (size_t)(row0 + ai * 128 + m * 16);
; #pragma unroll
;                 for (int bj = 0; bj < 2; ++bj) { const pg8::f32x4 v0 = acc[ai][bj][m][0], v1 = acc[ai][bj][m][1];
;                     const u32x4 gz = *(const u32x4*)(Z + row * DIN + goff + col0 + bj * 128); u32x4 w;
;                     w.x = pg8::cvt_pk_bf16(v0[0] * silu_f(bflo(gz.x)), v0[1] * silu_f(bfhi(gz.x))); w.y = pg8::cvt_pk_bf16(v0[2] * silu_f(bflo(gz.y)), v0[3] * silu_f(bfhi(gz.y)));
;                     w.z = pg8::cvt_pk_bf16(v1[0] * silu_f(bflo(gz.z)), v1[1] * silu_f(bfhi(gz.z))); w.w = pg8::cvt_pk_bf16(v1[2] * silu_f(bflo(gz.w)), v1[3] * silu_f(bfhi(gz.w)));
;                     *(u32x4*)(O + row * DM + coff + col0 + bj * 128) = w; } }
	v_lshlrev_b32_e32 v94, 16, v90
	v_mul_f32_e32 v95, 0xbfb8aa3b, v94
	v_exp_f32_e32 v95, v95
	v_and_b32_e32 v90, 0xffff0000, v90
	v_add_f32_e32 v95, 1.0, v95
	v_div_scale_f32 v96, s[12:13], v95, v95, v94
	v_rcp_f32_e32 v97, v96
	s_nop 0
	v_fma_f32 v100, -v96, v97, 1.0
	v_fmac_f32_e32 v97, v100, v97
	v_div_scale_f32 v100, vcc, v94, v95, v94
	v_mul_f32_e32 v101, v100, v97
	v_fma_f32 v102, -v96, v101, v100
	v_fmac_f32_e32 v101, v102, v97
	v_fma_f32 v96, -v96, v101, v100
	v_div_fmas_f32 v96, v96, v97, v101
	v_div_fixup_f32 v94, v96, v95, v94
	v_mul_f32_e32 v86, v86, v94
	v_mul_f32_e32 v94, 0xbfb8aa3b, v90
	v_exp_f32_e32 v94, v94
	s_nop 0
	v_add_f32_e32 v94, 1.0, v94
	v_div_scale_f32 v95, s[12:13], v94, v94, v90
	v_rcp_f32_e32 v96, v95
	s_nop 0
	v_fma_f32 v97, -v95, v96, 1.0
	v_fmac_f32_e32 v96, v97, v96
	v_div_scale_f32 v97, vcc, v90, v94, v90
	v_mul_f32_e32 v100, v97, v96
	v_fma_f32 v101, -v95, v100, v97
	v_fmac_f32_e32 v100, v101, v96
	v_fma_f32 v95, -v95, v100, v97
	v_div_fmas_f32 v95, v95, v96, v100
	v_div_fixup_f32 v90, v95, v94, v90
	v_mul_f32_e32 v87, v87, v90
	v_cvt_pk_bf16_f32 v86, v86, v87
	v_lshlrev_b32_e32 v87, 16, v91
	v_mul_f32_e32 v90, 0xbfb8aa3b, v87
	v_exp_f32_e32 v90, v90
	s_nop 0
	v_add_f32_e32 v90, 1.0, v90
	v_div_scale_f32 v94, s[12:13], v90, v90, v87
	v_rcp_f32_e32 v95, v94
	s_nop 0
	v_fma_f32 v96, -v94, v95, 1.0
	v_fmac_f32_e32 v95, v96, v95
	v_div_scale_f32 v96, vcc, v87, v90, v87
	v_mul_f32_e32 v97, v96, v95
	v_fma_f32 v100, -v94, v97, v96
	v_fmac_f32_e32 v97, v100, v95
	v_fma_f32 v94, -v94, v97, v96
	v_div_fmas_f32 v94, v94, v95, v97
	v_div_fixup_f32 v87, v94, v90, v87
	v_mul_f32_e32 v87, v88, v87
	v_and_b32_e32 v88, 0xffff0000, v91
	v_mul_f32_e32 v90, 0xbfb8aa3b, v88
	v_exp_f32_e32 v90, v90
	s_nop 0
	v_add_f32_e32 v90, 1.0, v90
	v_div_scale_f32 v91, s[12:13], v90, v90, v88
	v_rcp_f32_e32 v94, v91
	s_nop 0
	v_fma_f32 v95, -v91, v94, 1.0
	v_fmac_f32_e32 v94, v95, v94
	v_div_scale_f32 v95, vcc, v88, v90, v88
	v_mul_f32_e32 v96, v95, v94
	v_fma_f32 v97, -v91, v96, v95
	v_fmac_f32_e32 v96, v97, v94
	v_fma_f32 v91, -v91, v96, v95
	v_div_fmas_f32 v91, v91, v94, v96
	v_div_fixup_f32 v88, v91, v90, v88
	v_mul_f32_e32 v88, v89, v88
	v_cvt_pk_bf16_f32 v87, v87, v88
	v_lshlrev_b32_e32 v88, 16, v92
	v_mul_f32_e32 v89, 0xbfb8aa3b, v88
	v_exp_f32_e32 v89, v89
	s_nop 0
	v_add_f32_e32 v89, 1.0, v89
	v_div_scale_f32 v90, s[12:13], v89, v89, v88
	v_rcp_f32_e32 v91, v90
	s_nop 0
	v_fma_f32 v94, -v90, v91, 1.0
	v_fmac_f32_e32 v91, v94, v91
	v_div_scale_f32 v94, vcc, v88, v89, v88
	v_mul_f32_e32 v95, v94, v91
	v_fma_f32 v96, -v90, v95, v94
	v_fmac_f32_e32 v95, v96, v91
	v_fma_f32 v90, -v90, v95, v94
	v_div_fmas_f32 v90, v90, v91, v95
	v_div_fixup_f32 v88, v90, v89, v88
	v_mul_f32_e32 v82, v82, v88
	v_and_b32_e32 v88, 0xffff0000, v92
	v_mul_f32_e32 v89, 0xbfb8aa3b, v88
	v_exp_f32_e32 v89, v89
	s_nop 0
	v_add_f32_e32 v89, 1.0, v89
	v_div_scale_f32 v90, s[12:13], v89, v89, v88
	v_rcp_f32_e32 v91, v90
	s_nop 0
	v_fma_f32 v92, -v90, v91, 1.0
	v_fmac_f32_e32 v91, v92, v91
	v_div_scale_f32 v92, vcc, v88, v89, v88
	v_mul_f32_e32 v94, v92, v91
	v_fma_f32 v95, -v90, v94, v92
	v_fmac_f32_e32 v94, v95, v91
	v_fma_f32 v90, -v90, v94, v92
	v_div_fmas_f32 v90, v90, v91, v94
	v_div_fixup_f32 v88, v90, v89, v88
	v_mul_f32_e32 v83, v83, v88
	v_cvt_pk_bf16_f32 v88, v82, v83
	v_lshlrev_b32_e32 v82, 16, v93
	v_mul_f32_e32 v83, 0xbfb8aa3b, v82
	v_exp_f32_e32 v83, v83
	s_nop 0
	v_add_f32_e32 v83, 1.0, v83
	v_div_scale_f32 v89, s[12:13], v83, v83, v82
	v_rcp_f32_e32 v90, v89
	s_nop 0
	v_fma_f32 v91, -v89, v90, 1.0
	v_fmac_f32_e32 v90, v91, v90
	v_div_scale_f32 v91, vcc, v82, v83, v82
	v_mul_f32_e32 v92, v91, v90
	v_fma_f32 v94, -v89, v92, v91
	v_fmac_f32_e32 v92, v94, v90
	v_fma_f32 v89, -v89, v92, v91
	v_div_fmas_f32 v89, v89, v90, v92
	v_div_fixup_f32 v82, v89, v83, v82
	v_and_b32_e32 v83, 0xffff0000, v93
	v_mul_f32_e32 v82, v84, v82
	v_mul_f32_e32 v84, 0xbfb8aa3b, v83
	v_exp_f32_e32 v84, v84
	s_nop 0
	v_add_f32_e32 v84, 1.0, v84
	v_div_scale_f32 v89, s[12:13], v84, v84, v83
	v_rcp_f32_e32 v90, v89
	s_nop 0
	v_fma_f32 v91, -v89, v90, 1.0
	v_fmac_f32_e32 v90, v91, v90
	v_div_scale_f32 v91, vcc, v83, v84, v83
	v_mul_f32_e32 v92, v91, v90
	v_fma_f32 v93, -v89, v92, v91
	v_fmac_f32_e32 v92, v93, v90
	v_fma_f32 v89, -v89, v92, v91
	v_div_fmas_f32 v89, v89, v90, v92
	v_div_fixup_f32 v83, v89, v84, v83
	v_mul_f32_e32 v83, v85, v83
	v_cvt_pk_bf16_f32 v89, v82, v83
	v_or_b32_e32 v82, 48, v160
	v_ashrrev_i32_e32 v83, 31, v82
	global_store_dwordx4 v[98:99], v[86:89], off offset:256
	s_nop 1
	v_lshlrev_b64 v[86:87], 12, v[82:83]
	v_mad_i64_i32 v[82:83], s[12:13], v82, s75, v[162:163]
	v_lshl_add_u64 v[82:83], v[82:83], 0, v[144:145]
	v_lshl_add_u64 v[88:89], v[82:83], 0, s[26:27]
	v_add_co_u32_e32 v82, vcc, s5, v82
	s_nop 1
	v_addc_co_u32_e32 v83, vcc, 0, v83, vcc
	global_load_dwordx4 v[82:85], v[82:83], off
	s_waitcnt vmcnt(0)
; __device__ __forceinline__ unsigned cvt_pk_bf16(float lo, float hi) { unsigned r; asm volatile("v_cvt_pk_bf16_f32 %0, %1, %2" : "=v"(r) : "v"(lo), "v"(hi)); return r; }
; __device__ __forceinline__ float bflo(unsigned u) { return __uint_as_float(u << 16); }
; __device__ __forceinline__ float bfhi(unsigned u) { return __uint_as_float(u & 0xffff0000u); }
; __device__ __forceinline__ float silu_f(float v) { return v / (1.f + __expf(-v)); }
;     __device__ __forceinline__ void operator()(const pg8::f32x4 (&acc)[2][2][4][2], const pg8::Unit& u, int wr, int wc, int fr, int fq) const {
;     ...
;             for (int m = 0; m < 4; ++m) { const size_t row = (size_t)(row0 + ai * 128 + m * 16);
; #pragma unroll
;                 for (int bj = 0; bj < 2; ++bj) { const pg8::f32x4 v0 = acc[ai][bj][m][0], v1 = acc[ai][bj][m][1];
;                     const u32x4 gz = *(const u32x4*)(Z + row * DIN + goff + col0 + bj * 128); u32x4 w;
;                     w.x = pg8::cvt_pk_bf16(v0[0] * silu_f(bflo(gz.x)), v0[1] * silu_f(bfhi(gz.x))); w.y = pg8::cvt_pk_bf16(v0[2] * silu_f(bflo(gz.y)), v0[3] * silu_f(bfhi(gz.y)));
;                     w.z = pg8::cvt_pk_bf16(v1[0] * silu_f(bflo(gz.z)), v1[1] * silu_f(bfhi(gz.z))); w.w = pg8::cvt_pk_bf16(v1[2] * silu_f(bflo(gz.w)), v1[3] * silu_f(bfhi(gz.w)));
;                     *(u32x4*)(O + row * DM + coff + col0 + bj * 128) = w; } }
	v_lshlrev_b32_e32 v90, 16, v82
	v_mul_f32_e32 v91, 0xbfb8aa3b, v90
	v_exp_f32_e32 v91, v91
	v_and_b32_e32 v82, 0xffff0000, v82
	v_add_f32_e32 v91, 1.0, v91
	v_div_scale_f32 v92, s[12:13], v91, v91, v90
	v_rcp_f32_e32 v93, v92
	s_nop 0
	v_fma_f32 v94, -v92, v93, 1.0
	v_fmac_f32_e32 v93, v94, v93
	v_div_scale_f32 v94, vcc, v90, v91, v90
	v_mul_f32_e32 v95, v94, v93
	v_fma_f32 v96, -v92, v95, v94
	v_fmac_f32_e32 v95, v96, v93
	v_fma_f32 v92, -v92, v95, v94
	v_div_fmas_f32 v92, v92, v93, v95
	v_div_fixup_f32 v90, v92, v91, v90
	v_mul_f32_e32 v78, v78, v90
	v_mul_f32_e32 v90, 0xbfb8aa3b, v82
	v_exp_f32_e32 v90, v90
	s_nop 0
	v_add_f32_e32 v90, 1.0, v90
	v_div_scale_f32 v91, s[12:13], v90, v90, v82
	v_rcp_f32_e32 v92, v91
	s_nop 0
	v_fma_f32 v93, -v91, v92, 1.0
	v_fmac_f32_e32 v92, v93, v92
	v_div_scale_f32 v93, vcc, v82, v90, v82
	v_mul_f32_e32 v94, v93, v92
	v_fma_f32 v95, -v91, v94, v93
	v_fmac_f32_e32 v94, v95, v92
	v_fma_f32 v91, -v91, v94, v93
	v_div_fmas_f32 v91, v91, v92, v94
	v_div_fixup_f32 v82, v91, v90, v82
	v_mul_f32_e32 v79, v79, v82
	v_cvt_pk_bf16_f32 v78, v78, v79
	v_lshlrev_b32_e32 v79, 16, v83
	v_mul_f32_e32 v82, 0xbfb8aa3b, v79
	v_exp_f32_e32 v82, v82
	s_nop 0
	v_add_f32_e32 v82, 1.0, v82
	v_div_scale_f32 v90, s[12:13], v82, v82, v79
	v_rcp_f32_e32 v91, v90
	s_nop 0
	v_fma_f32 v92, -v90, v91, 1.0
	v_fmac_f32_e32 v91, v92, v91
	v_div_scale_f32 v92, vcc, v79, v82, v79
	v_mul_f32_e32 v93, v92, v91
	v_fma_f32 v94, -v90, v93, v92
	v_fmac_f32_e32 v93, v94, v91
	v_fma_f32 v90, -v90, v93, v92
	v_div_fmas_f32 v90, v90, v91, v93
	v_div_fixup_f32 v79, v90, v82, v79
	v_mul_f32_e32 v79, v80, v79
	v_and_b32_e32 v80, 0xffff0000, v83
	v_mul_f32_e32 v82, 0xbfb8aa3b, v80
	v_exp_f32_e32 v82, v82
	s_nop 0
	v_add_f32_e32 v82, 1.0, v82
	v_div_scale_f32 v83, s[12:13], v82, v82, v80
	v_rcp_f32_e32 v90, v83
	s_nop 0
	v_fma_f32 v91, -v83, v90, 1.0
	v_fmac_f32_e32 v90, v91, v90
	v_div_scale_f32 v91, vcc, v80, v82, v80
	v_mul_f32_e32 v92, v91, v90
	v_fma_f32 v93, -v83, v92, v91
	v_fmac_f32_e32 v92, v93, v90
	v_fma_f32 v83, -v83, v92, v91
	v_div_fmas_f32 v83, v83, v90, v92
	v_div_fixup_f32 v80, v83, v82, v80
	v_mul_f32_e32 v80, v81, v80
	v_cvt_pk_bf16_f32 v79, v79, v80
	v_lshlrev_b32_e32 v80, 16, v84
	v_mul_f32_e32 v81, 0xbfb8aa3b, v80
	v_exp_f32_e32 v81, v81
	s_nop 0
	v_add_f32_e32 v81, 1.0, v81
	v_div_scale_f32 v82, s[12:13], v81, v81, v80
	v_rcp_f32_e32 v83, v82
	s_nop 0
	v_fma_f32 v90, -v82, v83, 1.0
	v_fmac_f32_e32 v83, v90, v83
	v_div_scale_f32 v90, vcc, v80, v81, v80
	v_mul_f32_e32 v91, v90, v83
	v_fma_f32 v92, -v82, v91, v90
	v_fmac_f32_e32 v91, v92, v83
	v_fma_f32 v82, -v82, v91, v90
	v_div_fmas_f32 v82, v82, v83, v91
	v_div_fixup_f32 v80, v82, v81, v80
	v_mul_f32_e32 v74, v74, v80
	v_and_b32_e32 v80, 0xffff0000, v84
	v_mul_f32_e32 v81, 0xbfb8aa3b, v80
	v_exp_f32_e32 v81, v81
	s_nop 0
	v_add_f32_e32 v81, 1.0, v81
	v_div_scale_f32 v82, s[12:13], v81, v81, v80
	v_rcp_f32_e32 v83, v82
	s_nop 0
	v_fma_f32 v84, -v82, v83, 1.0
	v_fmac_f32_e32 v83, v84, v83
	v_div_scale_f32 v84, vcc, v80, v81, v80
	v_mul_f32_e32 v90, v84, v83
	v_fma_f32 v91, -v82, v90, v84
	v_fmac_f32_e32 v90, v91, v83
	v_fma_f32 v82, -v82, v90, v84
	v_div_fmas_f32 v82, v82, v83, v90
	v_div_fixup_f32 v80, v82, v81, v80
	v_mul_f32_e32 v75, v75, v80
	v_cvt_pk_bf16_f32 v80, v74, v75
	v_lshlrev_b32_e32 v74, 16, v85
	v_mul_f32_e32 v75, 0xbfb8aa3b, v74
	v_exp_f32_e32 v75, v75
	s_nop 0
	v_add_f32_e32 v75, 1.0, v75
	v_div_scale_f32 v81, s[12:13], v75, v75, v74
	v_rcp_f32_e32 v82, v81
	s_nop 0
	v_fma_f32 v83, -v81, v82, 1.0
	v_fmac_f32_e32 v82, v83, v82
	v_div_scale_f32 v83, vcc, v74, v75, v74
	v_mul_f32_e32 v84, v83, v82
	v_fma_f32 v90, -v81, v84, v83
	v_fmac_f32_e32 v84, v90, v82
	v_fma_f32 v81, -v81, v84, v83
	v_div_fmas_f32 v81, v81, v82, v84
	v_div_fixup_f32 v74, v81, v75, v74
	v_and_b32_e32 v75, 0xffff0000, v85
	v_mul_f32_e32 v74, v76, v74
	v_mul_f32_e32 v76, 0xbfb8aa3b, v75
	v_exp_f32_e32 v76, v76
	s_nop 0
	v_add_f32_e32 v76, 1.0, v76
	v_div_scale_f32 v81, s[12:13], v76, v76, v75
	v_rcp_f32_e32 v82, v81
	s_nop 0
	v_fma_f32 v83, -v81, v82, 1.0
	v_fmac_f32_e32 v82, v83, v82
	v_div_scale_f32 v83, vcc, v75, v76, v75
	v_mul_f32_e32 v84, v83, v82
	v_fma_f32 v85, -v81, v84, v83
	v_fmac_f32_e32 v84, v85, v82
	v_fma_f32 v81, -v81, v84, v83
	v_div_fmas_f32 v81, v81, v82, v84
	v_div_fixup_f32 v75, v81, v76, v75
	v_mul_f32_e32 v75, v77, v75
	v_cvt_pk_bf16_f32 v81, v74, v75
	v_lshl_add_u64 v[74:75], s[72:73], 0, v[86:87]
	v_lshl_add_u64 v[82:83], v[74:75], 0, v[144:145]
	global_load_dwordx4 v[74:77], v[88:89], off offset:256
	global_store_dwordx4 v[82:83], v[78:81], off
	s_waitcnt vmcnt(1)
; __device__ __forceinline__ unsigned cvt_pk_bf16(float lo, float hi) { unsigned r; asm volatile("v_cvt_pk_bf16_f32 %0, %1, %2" : "=v"(r) : "v"(lo), "v"(hi)); return r; }
; __device__ __forceinline__ float bflo(unsigned u) { return __uint_as_float(u << 16); }
; __device__ __forceinline__ float bfhi(unsigned u) { return __uint_as_float(u & 0xffff0000u); }
; __device__ __forceinline__ float silu_f(float v) { return v / (1.f + __expf(-v)); }
;     __device__ __forceinline__ void operator()(const pg8::f32x4 (&acc)[2][2][4][2], const pg8::Unit& u, int wr, int wc, int fr, int fq) const {
;     ...
;             for (int m = 0; m < 4; ++m) { const size_t row = (size_t)(row0 + ai * 128 + m * 16);
; #pragma unroll
;                 for (int bj = 0; bj < 2; ++bj) { const pg8::f32x4 v0 = acc[ai][bj][m][0], v1 = acc[ai][bj][m][1];
;                     const u32x4 gz = *(const u32x4*)(Z + row * DIN + goff + col0 + bj * 128); u32x4 w;
;                     w.x = pg8::cvt_pk_bf16(v0[0] * silu_f(bflo(gz.x)), v0[1] * silu_f(bfhi(gz.x))); w.y = pg8::cvt_pk_bf16(v0[2] * silu_f(bflo(gz.y)), v0[3] * silu_f(bfhi(gz.y)));
;                     w.z = pg8::cvt_pk_bf16(v1[0] * silu_f(bflo(gz.z)), v1[1] * silu_f(bfhi(gz.z))); w.w = pg8::cvt_pk_bf16(v1[2] * silu_f(bflo(gz.w)), v1[3] * silu_f(bfhi(gz.w)));
;                     *(u32x4*)(O + row * DM + coff + col0 + bj * 128) = w; } }
	v_lshlrev_b32_e32 v78, 16, v74
	v_mul_f32_e32 v79, 0xbfb8aa3b, v78
	v_exp_f32_e32 v79, v79
	v_and_b32_e32 v74, 0xffff0000, v74
	v_add_f32_e32 v79, 1.0, v79
	v_div_scale_f32 v80, s[12:13], v79, v79, v78
	v_rcp_f32_e32 v81, v80
	s_nop 0
	v_fma_f32 v84, -v80, v81, 1.0
	v_fmac_f32_e32 v81, v84, v81
	v_div_scale_f32 v84, vcc, v78, v79, v78
	v_mul_f32_e32 v85, v84, v81
	v_fma_f32 v86, -v80, v85, v84
	v_fmac_f32_e32 v85, v86, v81
	v_fma_f32 v80, -v80, v85, v84
	v_div_fmas_f32 v80, v80, v81, v85
	v_div_fixup_f32 v78, v80, v79, v78
	v_mul_f32_e32 v70, v70, v78
	v_mul_f32_e32 v78, 0xbfb8aa3b, v74
	v_exp_f32_e32 v78, v78
	s_nop 0
	v_add_f32_e32 v78, 1.0, v78
	v_div_scale_f32 v79, s[12:13], v78, v78, v74
	v_rcp_f32_e32 v80, v79
	s_nop 0
	v_fma_f32 v81, -v79, v80, 1.0
	v_fmac_f32_e32 v80, v81, v80
	v_div_scale_f32 v81, vcc, v74, v78, v74
	v_mul_f32_e32 v84, v81, v80
	v_fma_f32 v85, -v79, v84, v81
	v_fmac_f32_e32 v84, v85, v80
	v_fma_f32 v79, -v79, v84, v81
	v_div_fmas_f32 v79, v79, v80, v84
	v_div_fixup_f32 v74, v79, v78, v74
	v_mul_f32_e32 v71, v71, v74
	v_cvt_pk_bf16_f32 v70, v70, v71
	v_lshlrev_b32_e32 v71, 16, v75
	v_mul_f32_e32 v74, 0xbfb8aa3b, v71
	v_exp_f32_e32 v74, v74
	s_nop 0
	v_add_f32_e32 v74, 1.0, v74
	v_div_scale_f32 v78, s[12:13], v74, v74, v71
	v_rcp_f32_e32 v79, v78
	s_nop 0
	v_fma_f32 v80, -v78, v79, 1.0
	v_fmac_f32_e32 v79, v80, v79
	v_div_scale_f32 v80, vcc, v71, v74, v71
	v_mul_f32_e32 v81, v80, v79
	v_fma_f32 v84, -v78, v81, v80
	v_fmac_f32_e32 v81, v84, v79
	v_fma_f32 v78, -v78, v81, v80
	v_div_fmas_f32 v78, v78, v79, v81
	v_div_fixup_f32 v71, v78, v74, v71
	v_mul_f32_e32 v71, v72, v71
	v_and_b32_e32 v72, 0xffff0000, v75
	v_mul_f32_e32 v74, 0xbfb8aa3b, v72
	v_exp_f32_e32 v74, v74
	s_nop 0
	v_add_f32_e32 v74, 1.0, v74
	v_div_scale_f32 v75, s[12:13], v74, v74, v72
	v_rcp_f32_e32 v78, v75
	s_nop 0
	v_fma_f32 v79, -v75, v78, 1.0
	v_fmac_f32_e32 v78, v79, v78
	v_div_scale_f32 v79, vcc, v72, v74, v72
	v_mul_f32_e32 v80, v79, v78
	v_fma_f32 v81, -v75, v80, v79
	v_fmac_f32_e32 v80, v81, v78
	v_fma_f32 v75, -v75, v80, v79
	v_div_fmas_f32 v75, v75, v78, v80
	v_div_fixup_f32 v72, v75, v74, v72
	v_mul_f32_e32 v72, v73, v72
	v_cvt_pk_bf16_f32 v71, v71, v72
	v_lshlrev_b32_e32 v72, 16, v76
	v_mul_f32_e32 v73, 0xbfb8aa3b, v72
	v_exp_f32_e32 v73, v73
	s_nop 0
	v_add_f32_e32 v73, 1.0, v73
	v_div_scale_f32 v74, s[12:13], v73, v73, v72
	v_rcp_f32_e32 v75, v74
	s_nop 0
	v_fma_f32 v78, -v74, v75, 1.0
	v_fmac_f32_e32 v75, v78, v75
	v_div_scale_f32 v78, vcc, v72, v73, v72
	v_mul_f32_e32 v79, v78, v75
	v_fma_f32 v80, -v74, v79, v78
	v_fmac_f32_e32 v79, v80, v75
	v_fma_f32 v74, -v74, v79, v78
	v_div_fmas_f32 v74, v74, v75, v79
	v_div_fixup_f32 v72, v74, v73, v72
	v_mul_f32_e32 v66, v66, v72
	v_and_b32_e32 v72, 0xffff0000, v76
	v_mul_f32_e32 v73, 0xbfb8aa3b, v72
	v_exp_f32_e32 v73, v73
	s_nop 0
	v_add_f32_e32 v73, 1.0, v73
	v_div_scale_f32 v74, s[12:13], v73, v73, v72
	v_rcp_f32_e32 v75, v74
	s_nop 0
	v_fma_f32 v76, -v74, v75, 1.0
	v_fmac_f32_e32 v75, v76, v75
	v_div_scale_f32 v76, vcc, v72, v73, v72
	v_mul_f32_e32 v78, v76, v75
	v_fma_f32 v79, -v74, v78, v76
	v_fmac_f32_e32 v78, v79, v75
	v_fma_f32 v74, -v74, v78, v76
	v_div_fmas_f32 v74, v74, v75, v78
	v_div_fixup_f32 v72, v74, v73, v72
	v_mul_f32_e32 v67, v67, v72
	v_cvt_pk_bf16_f32 v72, v66, v67
	v_lshlrev_b32_e32 v66, 16, v77
	v_mul_f32_e32 v67, 0xbfb8aa3b, v66
	v_exp_f32_e32 v67, v67
	s_nop 0
	v_add_f32_e32 v67, 1.0, v67
	v_div_scale_f32 v73, s[12:13], v67, v67, v66
	v_rcp_f32_e32 v74, v73
	s_nop 0
	v_fma_f32 v75, -v73, v74, 1.0
	v_fmac_f32_e32 v74, v75, v74
	v_div_scale_f32 v75, vcc, v66, v67, v66
	v_mul_f32_e32 v76, v75, v74
	v_fma_f32 v78, -v73, v76, v75
	v_fmac_f32_e32 v76, v78, v74
	v_fma_f32 v73, -v73, v76, v75
	v_div_fmas_f32 v73, v73, v74, v76
	v_div_fixup_f32 v66, v73, v67, v66
	v_and_b32_e32 v67, 0xffff0000, v77
	v_mul_f32_e32 v66, v68, v66
	v_mul_f32_e32 v68, 0xbfb8aa3b, v67
	v_exp_f32_e32 v68, v68
	s_nop 0
	v_add_f32_e32 v68, 1.0, v68
	v_div_scale_f32 v73, s[12:13], v68, v68, v67
	v_rcp_f32_e32 v74, v73
	s_nop 0
	v_fma_f32 v75, -v73, v74, 1.0
	v_fmac_f32_e32 v74, v75, v74
	v_div_scale_f32 v75, vcc, v67, v68, v67
	v_mul_f32_e32 v76, v75, v74
	v_fma_f32 v77, -v73, v76, v75
	v_fmac_f32_e32 v76, v77, v74
	v_fma_f32 v73, -v73, v76, v75
	v_div_fmas_f32 v73, v73, v74, v76
	v_div_fixup_f32 v67, v73, v68, v67
	v_mul_f32_e32 v67, v69, v67
	v_cvt_pk_bf16_f32 v73, v66, v67
	v_add_u32_e32 v66, 0x80, v160
	v_ashrrev_i32_e32 v67, 31, v66
	global_store_dwordx4 v[82:83], v[70:73], off offset:256
	s_nop 1
	v_lshlrev_b64 v[70:71], 12, v[66:67]
	v_mad_i64_i32 v[66:67], s[12:13], v66, s75, v[162:163]
	v_lshl_add_u64 v[66:67], v[66:67], 0, v[144:145]
	v_lshl_add_u64 v[72:73], v[66:67], 0, s[26:27]
	v_add_co_u32_e32 v66, vcc, s5, v66
	s_nop 1
	v_addc_co_u32_e32 v67, vcc, 0, v67, vcc
	global_load_dwordx4 v[66:69], v[66:67], off
	s_waitcnt vmcnt(0)
; __device__ __forceinline__ unsigned cvt_pk_bf16(float lo, float hi) { unsigned r; asm volatile("v_cvt_pk_bf16_f32 %0, %1, %2" : "=v"(r) : "v"(lo), "v"(hi)); return r; }
; __device__ __forceinline__ float bflo(unsigned u) { return __uint_as_float(u << 16); }
; __device__ __forceinline__ float bfhi(unsigned u) { return __uint_as_float(u & 0xffff0000u); }
; __device__ __forceinline__ float silu_f(float v) { return v / (1.f + __expf(-v)); }
;     __device__ __forceinline__ void operator()(const pg8::f32x4 (&acc)[2][2][4][2], const pg8::Unit& u, int wr, int wc, int fr, int fq) const {
;     ...
;             for (int m = 0; m < 4; ++m) { const size_t row = (size_t)(row0 + ai * 128 + m * 16);
; #pragma unroll
;                 for (int bj = 0; bj < 2; ++bj) { const pg8::f32x4 v0 = acc[ai][bj][m][0], v1 = acc[ai][bj][m][1];
;                     const u32x4 gz = *(const u32x4*)(Z + row * DIN + goff + col0 + bj * 128); u32x4 w;
;                     w.x = pg8::cvt_pk_bf16(v0[0] * silu_f(bflo(gz.x)), v0[1] * silu_f(bfhi(gz.x))); w.y = pg8::cvt_pk_bf16(v0[2] * silu_f(bflo(gz.y)), v0[3] * silu_f(bfhi(gz.y)));
;                     w.z = pg8::cvt_pk_bf16(v1[0] * silu_f(bflo(gz.z)), v1[1] * silu_f(bfhi(gz.z))); w.w = pg8::cvt_pk_bf16(v1[2] * silu_f(bflo(gz.w)), v1[3] * silu_f(bfhi(gz.w)));
;                     *(u32x4*)(O + row * DM + coff + col0 + bj * 128) = w; } }
	v_lshlrev_b32_e32 v74, 16, v66
	v_mul_f32_e32 v75, 0xbfb8aa3b, v74
	v_exp_f32_e32 v75, v75
	v_and_b32_e32 v66, 0xffff0000, v66
	v_add_f32_e32 v75, 1.0, v75
	v_div_scale_f32 v76, s[12:13], v75, v75, v74
	v_rcp_f32_e32 v77, v76
	s_nop 0
	v_fma_f32 v78, -v76, v77, 1.0
	v_fmac_f32_e32 v77, v78, v77
	v_div_scale_f32 v78, vcc, v74, v75, v74
	v_mul_f32_e32 v79, v78, v77
	v_fma_f32 v80, -v76, v79, v78
	v_fmac_f32_e32 v79, v80, v77
	v_fma_f32 v76, -v76, v79, v78
	v_div_fmas_f32 v76, v76, v77, v79
	v_div_fixup_f32 v74, v76, v75, v74
	v_mul_f32_e32 v62, v62, v74
	v_mul_f32_e32 v74, 0xbfb8aa3b, v66
	v_exp_f32_e32 v74, v74
	s_nop 0
	v_add_f32_e32 v74, 1.0, v74
	v_div_scale_f32 v75, s[12:13], v74, v74, v66
	v_rcp_f32_e32 v76, v75
	s_nop 0
	v_fma_f32 v77, -v75, v76, 1.0
	v_fmac_f32_e32 v76, v77, v76
	v_div_scale_f32 v77, vcc, v66, v74, v66
	v_mul_f32_e32 v78, v77, v76
	v_fma_f32 v79, -v75, v78, v77
	v_fmac_f32_e32 v78, v79, v76
	v_fma_f32 v75, -v75, v78, v77
	v_div_fmas_f32 v75, v75, v76, v78
	v_div_fixup_f32 v66, v75, v74, v66
	v_mul_f32_e32 v63, v63, v66
	v_cvt_pk_bf16_f32 v62, v62, v63
	v_lshlrev_b32_e32 v63, 16, v67
	v_mul_f32_e32 v66, 0xbfb8aa3b, v63
	v_exp_f32_e32 v66, v66
	s_nop 0
	v_add_f32_e32 v66, 1.0, v66
	v_div_scale_f32 v74, s[12:13], v66, v66, v63
	v_rcp_f32_e32 v75, v74
	s_nop 0
	v_fma_f32 v76, -v74, v75, 1.0
	v_fmac_f32_e32 v75, v76, v75
	v_div_scale_f32 v76, vcc, v63, v66, v63
	v_mul_f32_e32 v77, v76, v75
	v_fma_f32 v78, -v74, v77, v76
	v_fmac_f32_e32 v77, v78, v75
	v_fma_f32 v74, -v74, v77, v76
	v_div_fmas_f32 v74, v74, v75, v77
	v_div_fixup_f32 v63, v74, v66, v63
	v_mul_f32_e32 v63, v64, v63
	v_and_b32_e32 v64, 0xffff0000, v67
	v_mul_f32_e32 v66, 0xbfb8aa3b, v64
	v_exp_f32_e32 v66, v66
	s_nop 0
	v_add_f32_e32 v66, 1.0, v66
	v_div_scale_f32 v67, s[12:13], v66, v66, v64
	v_rcp_f32_e32 v74, v67
	s_nop 0
	v_fma_f32 v75, -v67, v74, 1.0
	v_fmac_f32_e32 v74, v75, v74
	v_div_scale_f32 v75, vcc, v64, v66, v64
	v_mul_f32_e32 v76, v75, v74
	v_fma_f32 v77, -v67, v76, v75
	v_fmac_f32_e32 v76, v77, v74
	v_fma_f32 v67, -v67, v76, v75
	v_div_fmas_f32 v67, v67, v74, v76
	v_div_fixup_f32 v64, v67, v66, v64
	v_mul_f32_e32 v64, v65, v64
	v_cvt_pk_bf16_f32 v63, v63, v64
	v_lshlrev_b32_e32 v64, 16, v68
	v_mul_f32_e32 v65, 0xbfb8aa3b, v64
	v_exp_f32_e32 v65, v65
	s_nop 0
	v_add_f32_e32 v65, 1.0, v65
	v_div_scale_f32 v66, s[12:13], v65, v65, v64
	v_rcp_f32_e32 v67, v66
	s_nop 0
	v_fma_f32 v74, -v66, v67, 1.0
	v_fmac_f32_e32 v67, v74, v67
	v_div_scale_f32 v74, vcc, v64, v65, v64
	v_mul_f32_e32 v75, v74, v67
	v_fma_f32 v76, -v66, v75, v74
	v_fmac_f32_e32 v75, v76, v67
	v_fma_f32 v66, -v66, v75, v74
	v_div_fmas_f32 v66, v66, v67, v75
	v_div_fixup_f32 v64, v66, v65, v64
	v_mul_f32_e32 v58, v58, v64
	v_and_b32_e32 v64, 0xffff0000, v68
	v_mul_f32_e32 v65, 0xbfb8aa3b, v64
	v_exp_f32_e32 v65, v65
	s_nop 0
	v_add_f32_e32 v65, 1.0, v65
	v_div_scale_f32 v66, s[12:13], v65, v65, v64
	v_rcp_f32_e32 v67, v66
	s_nop 0
	v_fma_f32 v68, -v66, v67, 1.0
	v_fmac_f32_e32 v67, v68, v67
	v_div_scale_f32 v68, vcc, v64, v65, v64
	v_mul_f32_e32 v74, v68, v67
	v_fma_f32 v75, -v66, v74, v68
	v_fmac_f32_e32 v74, v75, v67
	v_fma_f32 v66, -v66, v74, v68
	v_div_fmas_f32 v66, v66, v67, v74
	v_div_fixup_f32 v64, v66, v65, v64
	v_mul_f32_e32 v59, v59, v64
	v_cvt_pk_bf16_f32 v64, v58, v59
	v_lshlrev_b32_e32 v58, 16, v69
	v_mul_f32_e32 v59, 0xbfb8aa3b, v58
	v_exp_f32_e32 v59, v59
	s_nop 0
	v_add_f32_e32 v59, 1.0, v59
	v_div_scale_f32 v65, s[12:13], v59, v59, v58
	v_rcp_f32_e32 v66, v65
	s_nop 0
	v_fma_f32 v67, -v65, v66, 1.0
	v_fmac_f32_e32 v66, v67, v66
	v_div_scale_f32 v67, vcc, v58, v59, v58
	v_mul_f32_e32 v68, v67, v66
	v_fma_f32 v74, -v65, v68, v67
	v_fmac_f32_e32 v68, v74, v66
	v_fma_f32 v65, -v65, v68, v67
	v_div_fmas_f32 v65, v65, v66, v68
	v_div_fixup_f32 v58, v65, v59, v58
	v_and_b32_e32 v59, 0xffff0000, v69
	v_mul_f32_e32 v58, v60, v58
	v_mul_f32_e32 v60, 0xbfb8aa3b, v59
	v_exp_f32_e32 v60, v60
	s_nop 0
	v_add_f32_e32 v60, 1.0, v60
	v_div_scale_f32 v65, s[12:13], v60, v60, v59
	v_rcp_f32_e32 v66, v65
	s_nop 0
	v_fma_f32 v67, -v65, v66, 1.0
	v_fmac_f32_e32 v66, v67, v66
	v_div_scale_f32 v67, vcc, v59, v60, v59
	v_mul_f32_e32 v68, v67, v66
	v_fma_f32 v69, -v65, v68, v67
	v_fmac_f32_e32 v68, v69, v66
	v_fma_f32 v65, -v65, v68, v67
	v_div_fmas_f32 v65, v65, v66, v68
	v_div_fixup_f32 v59, v65, v60, v59
	v_mul_f32_e32 v59, v61, v59
	v_cvt_pk_bf16_f32 v65, v58, v59
	v_lshl_add_u64 v[58:59], s[72:73], 0, v[70:71]
	v_lshl_add_u64 v[66:67], v[58:59], 0, v[144:145]
	global_load_dwordx4 v[58:61], v[72:73], off offset:256
	global_store_dwordx4 v[66:67], v[62:65], off
	s_waitcnt vmcnt(1)
; __device__ __forceinline__ unsigned cvt_pk_bf16(float lo, float hi) { unsigned r; asm volatile("v_cvt_pk_bf16_f32 %0, %1, %2" : "=v"(r) : "v"(lo), "v"(hi)); return r; }
; __device__ __forceinline__ float bflo(unsigned u) { return __uint_as_float(u << 16); }
; __device__ __forceinline__ float bfhi(unsigned u) { return __uint_as_float(u & 0xffff0000u); }
; __device__ __forceinline__ float silu_f(float v) { return v / (1.f + __expf(-v)); }
;     __device__ __forceinline__ void operator()(const pg8::f32x4 (&acc)[2][2][4][2], const pg8::Unit& u, int wr, int wc, int fr, int fq) const {
;     ...
;             for (int m = 0; m < 4; ++m) { const size_t row = (size_t)(row0 + ai * 128 + m * 16);
; #pragma unroll
;                 for (int bj = 0; bj < 2; ++bj) { const pg8::f32x4 v0 = acc[ai][bj][m][0], v1 = acc[ai][bj][m][1];
;                     const u32x4 gz = *(const u32x4*)(Z + row * DIN + goff + col0 + bj * 128); u32x4 w;
;                     w.x = pg8::cvt_pk_bf16(v0[0] * silu_f(bflo(gz.x)), v0[1] * silu_f(bfhi(gz.x))); w.y = pg8::cvt_pk_bf16(v0[2] * silu_f(bflo(gz.y)), v0[3] * silu_f(bfhi(gz.y)));
;                     w.z = pg8::cvt_pk_bf16(v1[0] * silu_f(bflo(gz.z)), v1[1] * silu_f(bfhi(gz.z))); w.w = pg8::cvt_pk_bf16(v1[2] * silu_f(bflo(gz.w)), v1[3] * silu_f(bfhi(gz.w)));
;                     *(u32x4*)(O + row * DM + coff + col0 + bj * 128) = w; } }
	v_lshlrev_b32_e32 v62, 16, v58
	v_mul_f32_e32 v63, 0xbfb8aa3b, v62
	v_exp_f32_e32 v63, v63
	v_and_b32_e32 v58, 0xffff0000, v58
	v_add_f32_e32 v63, 1.0, v63
	v_div_scale_f32 v64, s[12:13], v63, v63, v62
	v_rcp_f32_e32 v65, v64
	s_nop 0
	v_fma_f32 v68, -v64, v65, 1.0
	v_fmac_f32_e32 v65, v68, v65
	v_div_scale_f32 v68, vcc, v62, v63, v62
	v_mul_f32_e32 v69, v68, v65
	v_fma_f32 v70, -v64, v69, v68
	v_fmac_f32_e32 v69, v70, v65
	v_fma_f32 v64, -v64, v69, v68
	v_div_fmas_f32 v64, v64, v65, v69
	v_div_fixup_f32 v62, v64, v63, v62
	v_mul_f32_e32 v54, v54, v62
	v_mul_f32_e32 v62, 0xbfb8aa3b, v58
	v_exp_f32_e32 v62, v62
	s_nop 0
	v_add_f32_e32 v62, 1.0, v62
	v_div_scale_f32 v63, s[12:13], v62, v62, v58
	v_rcp_f32_e32 v64, v63
	s_nop 0
	v_fma_f32 v65, -v63, v64, 1.0
	v_fmac_f32_e32 v64, v65, v64
	v_div_scale_f32 v65, vcc, v58, v62, v58
	v_mul_f32_e32 v68, v65, v64
	v_fma_f32 v69, -v63, v68, v65
	v_fmac_f32_e32 v68, v69, v64
	v_fma_f32 v63, -v63, v68, v65
	v_div_fmas_f32 v63, v63, v64, v68
	v_div_fixup_f32 v58, v63, v62, v58
	v_mul_f32_e32 v55, v55, v58
	v_cvt_pk_bf16_f32 v54, v54, v55
	v_lshlrev_b32_e32 v55, 16, v59
	v_mul_f32_e32 v58, 0xbfb8aa3b, v55
	v_exp_f32_e32 v58, v58
	s_nop 0
	v_add_f32_e32 v58, 1.0, v58
	v_div_scale_f32 v62, s[12:13], v58, v58, v55
	v_rcp_f32_e32 v63, v62
	s_nop 0
	v_fma_f32 v64, -v62, v63, 1.0
	v_fmac_f32_e32 v63, v64, v63
	v_div_scale_f32 v64, vcc, v55, v58, v55
	v_mul_f32_e32 v65, v64, v63
	v_fma_f32 v68, -v62, v65, v64
	v_fmac_f32_e32 v65, v68, v63
	v_fma_f32 v62, -v62, v65, v64
	v_div_fmas_f32 v62, v62, v63, v65
	v_div_fixup_f32 v55, v62, v58, v55
	v_mul_f32_e32 v55, v56, v55
	v_and_b32_e32 v56, 0xffff0000, v59
	v_mul_f32_e32 v58, 0xbfb8aa3b, v56
	v_exp_f32_e32 v58, v58
	s_nop 0
	v_add_f32_e32 v58, 1.0, v58
	v_div_scale_f32 v59, s[12:13], v58, v58, v56
	v_rcp_f32_e32 v62, v59
	s_nop 0
	v_fma_f32 v63, -v59, v62, 1.0
	v_fmac_f32_e32 v62, v63, v62
	v_div_scale_f32 v63, vcc, v56, v58, v56
	v_mul_f32_e32 v64, v63, v62
	v_fma_f32 v65, -v59, v64, v63
	v_fmac_f32_e32 v64, v65, v62
	v_fma_f32 v59, -v59, v64, v63
	v_div_fmas_f32 v59, v59, v62, v64
	v_div_fixup_f32 v56, v59, v58, v56
	v_mul_f32_e32 v56, v57, v56
	v_cvt_pk_bf16_f32 v55, v55, v56
	v_lshlrev_b32_e32 v56, 16, v60
	v_mul_f32_e32 v57, 0xbfb8aa3b, v56
	v_exp_f32_e32 v57, v57
	s_nop 0
	v_add_f32_e32 v57, 1.0, v57
	v_div_scale_f32 v58, s[12:13], v57, v57, v56
	v_rcp_f32_e32 v59, v58
	s_nop 0
	v_fma_f32 v62, -v58, v59, 1.0
	v_fmac_f32_e32 v59, v62, v59
	v_div_scale_f32 v62, vcc, v56, v57, v56
	v_mul_f32_e32 v63, v62, v59
	v_fma_f32 v64, -v58, v63, v62
	v_fmac_f32_e32 v63, v64, v59
	v_fma_f32 v58, -v58, v63, v62
	v_div_fmas_f32 v58, v58, v59, v63
	v_div_fixup_f32 v56, v58, v57, v56
	v_mul_f32_e32 v50, v50, v56
	v_and_b32_e32 v56, 0xffff0000, v60
	v_mul_f32_e32 v57, 0xbfb8aa3b, v56
	v_exp_f32_e32 v57, v57
	s_nop 0
	v_add_f32_e32 v57, 1.0, v57
	v_div_scale_f32 v58, s[12:13], v57, v57, v56
	v_rcp_f32_e32 v59, v58
	s_nop 0
	v_fma_f32 v60, -v58, v59, 1.0
	v_fmac_f32_e32 v59, v60, v59
	v_div_scale_f32 v60, vcc, v56, v57, v56
	v_mul_f32_e32 v62, v60, v59
	v_fma_f32 v63, -v58, v62, v60
	v_fmac_f32_e32 v62, v63, v59
	v_fma_f32 v58, -v58, v62, v60
	v_div_fmas_f32 v58, v58, v59, v62
	v_div_fixup_f32 v56, v58, v57, v56
	v_mul_f32_e32 v51, v51, v56
	v_cvt_pk_bf16_f32 v56, v50, v51
	v_lshlrev_b32_e32 v50, 16, v61
	v_mul_f32_e32 v51, 0xbfb8aa3b, v50
	v_exp_f32_e32 v51, v51
	s_nop 0
	v_add_f32_e32 v51, 1.0, v51
	v_div_scale_f32 v57, s[12:13], v51, v51, v50
	v_rcp_f32_e32 v58, v57
	s_nop 0
	v_fma_f32 v59, -v57, v58, 1.0
	v_fmac_f32_e32 v58, v59, v58
	v_div_scale_f32 v59, vcc, v50, v51, v50
	v_mul_f32_e32 v60, v59, v58
	v_fma_f32 v62, -v57, v60, v59
	v_fmac_f32_e32 v60, v62, v58
	v_fma_f32 v57, -v57, v60, v59
	v_div_fmas_f32 v57, v57, v58, v60
	v_div_fixup_f32 v50, v57, v51, v50
	v_and_b32_e32 v51, 0xffff0000, v61
	v_mul_f32_e32 v50, v52, v50
	v_mul_f32_e32 v52, 0xbfb8aa3b, v51
	v_exp_f32_e32 v52, v52
	s_nop 0
	v_add_f32_e32 v52, 1.0, v52
	v_div_scale_f32 v57, s[12:13], v52, v52, v51
	v_rcp_f32_e32 v58, v57
	s_nop 0
	v_fma_f32 v59, -v57, v58, 1.0
	v_fmac_f32_e32 v58, v59, v58
	v_div_scale_f32 v59, vcc, v51, v52, v51
	v_mul_f32_e32 v60, v59, v58
	v_fma_f32 v61, -v57, v60, v59
	v_fmac_f32_e32 v60, v61, v58
	v_fma_f32 v57, -v57, v60, v59
	v_div_fmas_f32 v57, v57, v58, v60
	v_div_fixup_f32 v51, v57, v52, v51
	v_mul_f32_e32 v51, v53, v51
	v_cvt_pk_bf16_f32 v57, v50, v51
	v_add_u32_e32 v50, 0x90, v160
	v_ashrrev_i32_e32 v51, 31, v50
	global_store_dwordx4 v[66:67], v[54:57], off offset:256
	s_nop 1
	v_lshlrev_b64 v[54:55], 12, v[50:51]
	v_mad_i64_i32 v[50:51], s[12:13], v50, s75, v[162:163]
	v_lshl_add_u64 v[50:51], v[50:51], 0, v[144:145]
	v_lshl_add_u64 v[56:57], v[50:51], 0, s[26:27]
	v_add_co_u32_e32 v50, vcc, s5, v50
	s_nop 1
	v_addc_co_u32_e32 v51, vcc, 0, v51, vcc
	global_load_dwordx4 v[50:53], v[50:51], off
	s_waitcnt vmcnt(0)
; __device__ __forceinline__ unsigned cvt_pk_bf16(float lo, float hi) { unsigned r; asm volatile("v_cvt_pk_bf16_f32 %0, %1, %2" : "=v"(r) : "v"(lo), "v"(hi)); return r; }
; __device__ __forceinline__ float bflo(unsigned u) { return __uint_as_float(u << 16); }
; __device__ __forceinline__ float bfhi(unsigned u) { return __uint_as_float(u & 0xffff0000u); }
; __device__ __forceinline__ float silu_f(float v) { return v / (1.f + __expf(-v)); }
;     __device__ __forceinline__ void operator()(const pg8::f32x4 (&acc)[2][2][4][2], const pg8::Unit& u, int wr, int wc, int fr, int fq) const {
;     ...
;             for (int m = 0; m < 4; ++m) { const size_t row = (size_t)(row0 + ai * 128 + m * 16);
; #pragma unroll
;                 for (int bj = 0; bj < 2; ++bj) { const pg8::f32x4 v0 = acc[ai][bj][m][0], v1 = acc[ai][bj][m][1];
;                     const u32x4 gz = *(const u32x4*)(Z + row * DIN + goff + col0 + bj * 128); u32x4 w;
;                     w.x = pg8::cvt_pk_bf16(v0[0] * silu_f(bflo(gz.x)), v0[1] * silu_f(bfhi(gz.x))); w.y = pg8::cvt_pk_bf16(v0[2] * silu_f(bflo(gz.y)), v0[3] * silu_f(bfhi(gz.y)));
;                     w.z = pg8::cvt_pk_bf16(v1[0] * silu_f(bflo(gz.z)), v1[1] * silu_f(bfhi(gz.z))); w.w = pg8::cvt_pk_bf16(v1[2] * silu_f(bflo(gz.w)), v1[3] * silu_f(bfhi(gz.w)));
;                     *(u32x4*)(O + row * DM + coff + col0 + bj * 128) = w; } }
	v_lshlrev_b32_e32 v58, 16, v50
	v_mul_f32_e32 v59, 0xbfb8aa3b, v58
	v_exp_f32_e32 v59, v59
	v_and_b32_e32 v50, 0xffff0000, v50
	v_add_f32_e32 v59, 1.0, v59
	v_div_scale_f32 v60, s[12:13], v59, v59, v58
	v_rcp_f32_e32 v61, v60
	s_nop 0
	v_fma_f32 v62, -v60, v61, 1.0
	v_fmac_f32_e32 v61, v62, v61
	v_div_scale_f32 v62, vcc, v58, v59, v58
	v_mul_f32_e32 v63, v62, v61
	v_fma_f32 v64, -v60, v63, v62
	v_fmac_f32_e32 v63, v64, v61
	v_fma_f32 v60, -v60, v63, v62
	v_div_fmas_f32 v60, v60, v61, v63
	v_div_fixup_f32 v58, v60, v59, v58
	v_mul_f32_e32 v46, v46, v58
	v_mul_f32_e32 v58, 0xbfb8aa3b, v50
	v_exp_f32_e32 v58, v58
	s_nop 0
	v_add_f32_e32 v58, 1.0, v58
	v_div_scale_f32 v59, s[12:13], v58, v58, v50
	v_rcp_f32_e32 v60, v59
	s_nop 0
	v_fma_f32 v61, -v59, v60, 1.0
	v_fmac_f32_e32 v60, v61, v60
	v_div_scale_f32 v61, vcc, v50, v58, v50
	v_mul_f32_e32 v62, v61, v60
	v_fma_f32 v63, -v59, v62, v61
	v_fmac_f32_e32 v62, v63, v60
	v_fma_f32 v59, -v59, v62, v61
	v_div_fmas_f32 v59, v59, v60, v62
	v_div_fixup_f32 v50, v59, v58, v50
	v_mul_f32_e32 v47, v47, v50
	v_cvt_pk_bf16_f32 v46, v46, v47
	v_lshlrev_b32_e32 v47, 16, v51
	v_mul_f32_e32 v50, 0xbfb8aa3b, v47
	v_exp_f32_e32 v50, v50
	s_nop 0
	v_add_f32_e32 v50, 1.0, v50
	v_div_scale_f32 v58, s[12:13], v50, v50, v47
	v_rcp_f32_e32 v59, v58
	s_nop 0
	v_fma_f32 v60, -v58, v59, 1.0
	v_fmac_f32_e32 v59, v60, v59
	v_div_scale_f32 v60, vcc, v47, v50, v47
	v_mul_f32_e32 v61, v60, v59
	v_fma_f32 v62, -v58, v61, v60
	v_fmac_f32_e32 v61, v62, v59
	v_fma_f32 v58, -v58, v61, v60
	v_div_fmas_f32 v58, v58, v59, v61
	v_div_fixup_f32 v47, v58, v50, v47
	v_mul_f32_e32 v47, v48, v47
	v_and_b32_e32 v48, 0xffff0000, v51
	v_mul_f32_e32 v50, 0xbfb8aa3b, v48
	v_exp_f32_e32 v50, v50
	s_nop 0
	v_add_f32_e32 v50, 1.0, v50
	v_div_scale_f32 v51, s[12:13], v50, v50, v48
	v_rcp_f32_e32 v58, v51
	s_nop 0
	v_fma_f32 v59, -v51, v58, 1.0
	v_fmac_f32_e32 v58, v59, v58
	v_div_scale_f32 v59, vcc, v48, v50, v48
	v_mul_f32_e32 v60, v59, v58
	v_fma_f32 v61, -v51, v60, v59
	v_fmac_f32_e32 v60, v61, v58
	v_fma_f32 v51, -v51, v60, v59
	v_div_fmas_f32 v51, v51, v58, v60
	v_div_fixup_f32 v48, v51, v50, v48
	v_mul_f32_e32 v48, v49, v48
	v_cvt_pk_bf16_f32 v47, v47, v48
	v_lshlrev_b32_e32 v48, 16, v52
	v_mul_f32_e32 v49, 0xbfb8aa3b, v48
	v_exp_f32_e32 v49, v49
	s_nop 0
	v_add_f32_e32 v49, 1.0, v49
	v_div_scale_f32 v50, s[12:13], v49, v49, v48
	v_rcp_f32_e32 v51, v50
	s_nop 0
	v_fma_f32 v58, -v50, v51, 1.0
	v_fmac_f32_e32 v51, v58, v51
	v_div_scale_f32 v58, vcc, v48, v49, v48
	v_mul_f32_e32 v59, v58, v51
	v_fma_f32 v60, -v50, v59, v58
	v_fmac_f32_e32 v59, v60, v51
	v_fma_f32 v50, -v50, v59, v58
	v_div_fmas_f32 v50, v50, v51, v59
	v_div_fixup_f32 v48, v50, v49, v48
	v_mul_f32_e32 v42, v42, v48
	v_and_b32_e32 v48, 0xffff0000, v52
	v_mul_f32_e32 v49, 0xbfb8aa3b, v48
	v_exp_f32_e32 v49, v49
	s_nop 0
	v_add_f32_e32 v49, 1.0, v49
	v_div_scale_f32 v50, s[12:13], v49, v49, v48
	v_rcp_f32_e32 v51, v50
	s_nop 0
	v_fma_f32 v52, -v50, v51, 1.0
	v_fmac_f32_e32 v51, v52, v51
	v_div_scale_f32 v52, vcc, v48, v49, v48
	v_mul_f32_e32 v58, v52, v51
	v_fma_f32 v59, -v50, v58, v52
	v_fmac_f32_e32 v58, v59, v51
	v_fma_f32 v50, -v50, v58, v52
	v_div_fmas_f32 v50, v50, v51, v58
	v_div_fixup_f32 v48, v50, v49, v48
	v_mul_f32_e32 v43, v43, v48
	v_cvt_pk_bf16_f32 v48, v42, v43
	v_lshlrev_b32_e32 v42, 16, v53
	v_mul_f32_e32 v43, 0xbfb8aa3b, v42
	v_exp_f32_e32 v43, v43
	s_nop 0
	v_add_f32_e32 v43, 1.0, v43
	v_div_scale_f32 v49, s[12:13], v43, v43, v42
	v_rcp_f32_e32 v50, v49
	s_nop 0
	v_fma_f32 v51, -v49, v50, 1.0
	v_fmac_f32_e32 v50, v51, v50
	v_div_scale_f32 v51, vcc, v42, v43, v42
	v_mul_f32_e32 v52, v51, v50
	v_fma_f32 v58, -v49, v52, v51
	v_fmac_f32_e32 v52, v58, v50
	v_fma_f32 v49, -v49, v52, v51
	v_div_fmas_f32 v49, v49, v50, v52
	v_div_fixup_f32 v42, v49, v43, v42
	v_and_b32_e32 v43, 0xffff0000, v53
	v_mul_f32_e32 v42, v44, v42
	v_mul_f32_e32 v44, 0xbfb8aa3b, v43
	v_exp_f32_e32 v44, v44
	s_nop 0
	v_add_f32_e32 v44, 1.0, v44
	v_div_scale_f32 v49, s[12:13], v44, v44, v43
	v_rcp_f32_e32 v50, v49
	s_nop 0
	v_fma_f32 v51, -v49, v50, 1.0
	v_fmac_f32_e32 v50, v51, v50
	v_div_scale_f32 v51, vcc, v43, v44, v43
	v_mul_f32_e32 v52, v51, v50
	v_fma_f32 v53, -v49, v52, v51
	v_fmac_f32_e32 v52, v53, v50
	v_fma_f32 v49, -v49, v52, v51
	v_div_fmas_f32 v49, v49, v50, v52
	v_div_fixup_f32 v43, v49, v44, v43
	v_mul_f32_e32 v43, v45, v43
	v_cvt_pk_bf16_f32 v49, v42, v43
	v_lshl_add_u64 v[42:43], s[72:73], 0, v[54:55]
	v_lshl_add_u64 v[50:51], v[42:43], 0, v[144:145]
	global_load_dwordx4 v[42:45], v[56:57], off offset:256
	global_store_dwordx4 v[50:51], v[46:49], off
	s_waitcnt vmcnt(1)
; __device__ __forceinline__ unsigned cvt_pk_bf16(float lo, float hi) { unsigned r; asm volatile("v_cvt_pk_bf16_f32 %0, %1, %2" : "=v"(r) : "v"(lo), "v"(hi)); return r; }
; __device__ __forceinline__ float bflo(unsigned u) { return __uint_as_float(u << 16); }
; __device__ __forceinline__ float bfhi(unsigned u) { return __uint_as_float(u & 0xffff0000u); }
; __device__ __forceinline__ float silu_f(float v) { return v / (1.f + __expf(-v)); }
;     __device__ __forceinline__ void operator()(const pg8::f32x4 (&acc)[2][2][4][2], const pg8::Unit& u, int wr, int wc, int fr, int fq) const {
;     ...
;             for (int m = 0; m < 4; ++m) { const size_t row = (size_t)(row0 + ai * 128 + m * 16);
; #pragma unroll
;                 for (int bj = 0; bj < 2; ++bj) { const pg8::f32x4 v0 = acc[ai][bj][m][0], v1 = acc[ai][bj][m][1];
;                     const u32x4 gz = *(const u32x4*)(Z + row * DIN + goff + col0 + bj * 128); u32x4 w;
;                     w.x = pg8::cvt_pk_bf16(v0[0] * silu_f(bflo(gz.x)), v0[1] * silu_f(bfhi(gz.x))); w.y = pg8::cvt_pk_bf16(v0[2] * silu_f(bflo(gz.y)), v0[3] * silu_f(bfhi(gz.y)));
;                     w.z = pg8::cvt_pk_bf16(v1[0] * silu_f(bflo(gz.z)), v1[1] * silu_f(bfhi(gz.z))); w.w = pg8::cvt_pk_bf16(v1[2] * silu_f(bflo(gz.w)), v1[3] * silu_f(bfhi(gz.w)));
;                     *(u32x4*)(O + row * DM + coff + col0 + bj * 128) = w; } }
	v_lshlrev_b32_e32 v46, 16, v42
	v_mul_f32_e32 v47, 0xbfb8aa3b, v46
	v_exp_f32_e32 v47, v47
	v_and_b32_e32 v42, 0xffff0000, v42
	v_add_f32_e32 v47, 1.0, v47
	v_div_scale_f32 v48, s[12:13], v47, v47, v46
	v_rcp_f32_e32 v49, v48
	s_nop 0
	v_fma_f32 v52, -v48, v49, 1.0
	v_fmac_f32_e32 v49, v52, v49
	v_div_scale_f32 v52, vcc, v46, v47, v46
	v_mul_f32_e32 v53, v52, v49
	v_fma_f32 v54, -v48, v53, v52
	v_fmac_f32_e32 v53, v54, v49
	v_fma_f32 v48, -v48, v53, v52
	v_div_fmas_f32 v48, v48, v49, v53
	v_div_fixup_f32 v46, v48, v47, v46
	v_mul_f32_e32 v38, v38, v46
	v_mul_f32_e32 v46, 0xbfb8aa3b, v42
	v_exp_f32_e32 v46, v46
	s_nop 0
	v_add_f32_e32 v46, 1.0, v46
	v_div_scale_f32 v47, s[12:13], v46, v46, v42
	v_rcp_f32_e32 v48, v47
	s_nop 0
	v_fma_f32 v49, -v47, v48, 1.0
	v_fmac_f32_e32 v48, v49, v48
	v_div_scale_f32 v49, vcc, v42, v46, v42
	v_mul_f32_e32 v52, v49, v48
	v_fma_f32 v53, -v47, v52, v49
	v_fmac_f32_e32 v52, v53, v48
	v_fma_f32 v47, -v47, v52, v49
	v_div_fmas_f32 v47, v47, v48, v52
	v_div_fixup_f32 v42, v47, v46, v42
	v_mul_f32_e32 v39, v39, v42
	v_cvt_pk_bf16_f32 v38, v38, v39
	v_lshlrev_b32_e32 v39, 16, v43
	v_mul_f32_e32 v42, 0xbfb8aa3b, v39
	v_exp_f32_e32 v42, v42
	s_nop 0
	v_add_f32_e32 v42, 1.0, v42
	v_div_scale_f32 v46, s[12:13], v42, v42, v39
	v_rcp_f32_e32 v47, v46
	s_nop 0
	v_fma_f32 v48, -v46, v47, 1.0
	v_fmac_f32_e32 v47, v48, v47
	v_div_scale_f32 v48, vcc, v39, v42, v39
	v_mul_f32_e32 v49, v48, v47
	v_fma_f32 v52, -v46, v49, v48
	v_fmac_f32_e32 v49, v52, v47
	v_fma_f32 v46, -v46, v49, v48
	v_div_fmas_f32 v46, v46, v47, v49
	v_div_fixup_f32 v39, v46, v42, v39
	v_mul_f32_e32 v39, v40, v39
	v_and_b32_e32 v40, 0xffff0000, v43
	v_mul_f32_e32 v42, 0xbfb8aa3b, v40
	v_exp_f32_e32 v42, v42
	s_nop 0
	v_add_f32_e32 v42, 1.0, v42
	v_div_scale_f32 v43, s[12:13], v42, v42, v40
	v_rcp_f32_e32 v46, v43
	s_nop 0
	v_fma_f32 v47, -v43, v46, 1.0
	v_fmac_f32_e32 v46, v47, v46
	v_div_scale_f32 v47, vcc, v40, v42, v40
	v_mul_f32_e32 v48, v47, v46
	v_fma_f32 v49, -v43, v48, v47
	v_fmac_f32_e32 v48, v49, v46
	v_fma_f32 v43, -v43, v48, v47
	v_div_fmas_f32 v43, v43, v46, v48
	v_div_fixup_f32 v40, v43, v42, v40
	v_mul_f32_e32 v40, v41, v40
	v_cvt_pk_bf16_f32 v39, v39, v40
	v_lshlrev_b32_e32 v40, 16, v44
	v_mul_f32_e32 v41, 0xbfb8aa3b, v40
	v_exp_f32_e32 v41, v41
	s_nop 0
	v_add_f32_e32 v41, 1.0, v41
	v_div_scale_f32 v42, s[12:13], v41, v41, v40
	v_rcp_f32_e32 v43, v42
	s_nop 0
	v_fma_f32 v46, -v42, v43, 1.0
	v_fmac_f32_e32 v43, v46, v43
	v_div_scale_f32 v46, vcc, v40, v41, v40
	v_mul_f32_e32 v47, v46, v43
	v_fma_f32 v48, -v42, v47, v46
	v_fmac_f32_e32 v47, v48, v43
	v_fma_f32 v42, -v42, v47, v46
	v_div_fmas_f32 v42, v42, v43, v47
	v_div_fixup_f32 v40, v42, v41, v40
	v_mul_f32_e32 v34, v34, v40
	v_and_b32_e32 v40, 0xffff0000, v44
	v_mul_f32_e32 v41, 0xbfb8aa3b, v40
	v_exp_f32_e32 v41, v41
	s_nop 0
	v_add_f32_e32 v41, 1.0, v41
	v_div_scale_f32 v42, s[12:13], v41, v41, v40
	v_rcp_f32_e32 v43, v42
	s_nop 0
	v_fma_f32 v44, -v42, v43, 1.0
	v_fmac_f32_e32 v43, v44, v43
	v_div_scale_f32 v44, vcc, v40, v41, v40
	v_mul_f32_e32 v46, v44, v43
	v_fma_f32 v47, -v42, v46, v44
	v_fmac_f32_e32 v46, v47, v43
	v_fma_f32 v42, -v42, v46, v44
	v_div_fmas_f32 v42, v42, v43, v46
	v_div_fixup_f32 v40, v42, v41, v40
	v_mul_f32_e32 v35, v35, v40
	v_cvt_pk_bf16_f32 v40, v34, v35
	v_lshlrev_b32_e32 v34, 16, v45
	v_mul_f32_e32 v35, 0xbfb8aa3b, v34
	v_exp_f32_e32 v35, v35
	s_nop 0
	v_add_f32_e32 v35, 1.0, v35
	v_div_scale_f32 v41, s[12:13], v35, v35, v34
	v_rcp_f32_e32 v42, v41
	s_nop 0
	v_fma_f32 v43, -v41, v42, 1.0
	v_fmac_f32_e32 v42, v43, v42
	v_div_scale_f32 v43, vcc, v34, v35, v34
	v_mul_f32_e32 v44, v43, v42
	v_fma_f32 v46, -v41, v44, v43
	v_fmac_f32_e32 v44, v46, v42
	v_fma_f32 v41, -v41, v44, v43
	v_div_fmas_f32 v41, v41, v42, v44
	v_div_fixup_f32 v34, v41, v35, v34
	v_and_b32_e32 v35, 0xffff0000, v45
	v_mul_f32_e32 v34, v36, v34
	v_mul_f32_e32 v36, 0xbfb8aa3b, v35
	v_exp_f32_e32 v36, v36
	s_nop 0
	v_add_f32_e32 v36, 1.0, v36
	v_div_scale_f32 v41, s[12:13], v36, v36, v35
	v_rcp_f32_e32 v42, v41
	s_nop 0
	v_fma_f32 v43, -v41, v42, 1.0
	v_fmac_f32_e32 v42, v43, v42
	v_div_scale_f32 v43, vcc, v35, v36, v35
	v_mul_f32_e32 v44, v43, v42
	v_fma_f32 v45, -v41, v44, v43
	v_fmac_f32_e32 v44, v45, v42
	v_fma_f32 v41, -v41, v44, v43
	v_div_fmas_f32 v41, v41, v42, v44
	v_div_fixup_f32 v35, v41, v36, v35
	v_mul_f32_e32 v35, v37, v35
	v_cvt_pk_bf16_f32 v41, v34, v35
	v_add_u32_e32 v34, 0xa0, v160
	v_ashrrev_i32_e32 v35, 31, v34
	global_store_dwordx4 v[50:51], v[38:41], off offset:256
	s_nop 1
	v_lshlrev_b64 v[38:39], 12, v[34:35]
	v_mad_i64_i32 v[34:35], s[12:13], v34, s75, v[162:163]
	v_lshl_add_u64 v[34:35], v[34:35], 0, v[144:145]
	v_lshl_add_u64 v[40:41], v[34:35], 0, s[26:27]
	v_add_co_u32_e32 v34, vcc, s5, v34
	s_nop 1
	v_addc_co_u32_e32 v35, vcc, 0, v35, vcc
	global_load_dwordx4 v[34:37], v[34:35], off
	s_waitcnt vmcnt(0)
; __device__ __forceinline__ unsigned cvt_pk_bf16(float lo, float hi) { unsigned r; asm volatile("v_cvt_pk_bf16_f32 %0, %1, %2" : "=v"(r) : "v"(lo), "v"(hi)); return r; }
; __device__ __forceinline__ float bflo(unsigned u) { return __uint_as_float(u << 16); }
; __device__ __forceinline__ float bfhi(unsigned u) { return __uint_as_float(u & 0xffff0000u); }
; __device__ __forceinline__ float silu_f(float v) { return v / (1.f + __expf(-v)); }
;     __device__ __forceinline__ void operator()(const pg8::f32x4 (&acc)[2][2][4][2], const pg8::Unit& u, int wr, int wc, int fr, int fq) const {
;     ...
;             for (int m = 0; m < 4; ++m) { const size_t row = (size_t)(row0 + ai * 128 + m * 16);
; #pragma unroll
;                 for (int bj = 0; bj < 2; ++bj) { const pg8::f32x4 v0 = acc[ai][bj][m][0], v1 = acc[ai][bj][m][1];
;                     const u32x4 gz = *(const u32x4*)(Z + row * DIN + goff + col0 + bj * 128); u32x4 w;
;                     w.x = pg8::cvt_pk_bf16(v0[0] * silu_f(bflo(gz.x)), v0[1] * silu_f(bfhi(gz.x))); w.y = pg8::cvt_pk_bf16(v0[2] * silu_f(bflo(gz.y)), v0[3] * silu_f(bfhi(gz.y)));
;                     w.z = pg8::cvt_pk_bf16(v1[0] * silu_f(bflo(gz.z)), v1[1] * silu_f(bfhi(gz.z))); w.w = pg8::cvt_pk_bf16(v1[2] * silu_f(bflo(gz.w)), v1[3] * silu_f(bfhi(gz.w)));
;                     *(u32x4*)(O + row * DM + coff + col0 + bj * 128) = w; } }
	v_lshlrev_b32_e32 v42, 16, v34
	v_mul_f32_e32 v43, 0xbfb8aa3b, v42
	v_exp_f32_e32 v43, v43
	v_and_b32_e32 v34, 0xffff0000, v34
	v_add_f32_e32 v43, 1.0, v43
	v_div_scale_f32 v44, s[12:13], v43, v43, v42
	v_rcp_f32_e32 v45, v44
	s_nop 0
	v_fma_f32 v46, -v44, v45, 1.0
	v_fmac_f32_e32 v45, v46, v45
	v_div_scale_f32 v46, vcc, v42, v43, v42
	v_mul_f32_e32 v47, v46, v45
	v_fma_f32 v48, -v44, v47, v46
	v_fmac_f32_e32 v47, v48, v45
	v_fma_f32 v44, -v44, v47, v46
	v_div_fmas_f32 v44, v44, v45, v47
	v_div_fixup_f32 v42, v44, v43, v42
	v_mul_f32_e32 v30, v30, v42
	v_mul_f32_e32 v42, 0xbfb8aa3b, v34
	v_exp_f32_e32 v42, v42
	s_nop 0
	v_add_f32_e32 v42, 1.0, v42
	v_div_scale_f32 v43, s[12:13], v42, v42, v34
	v_rcp_f32_e32 v44, v43
	s_nop 0
	v_fma_f32 v45, -v43, v44, 1.0
	v_fmac_f32_e32 v44, v45, v44
	v_div_scale_f32 v45, vcc, v34, v42, v34
	v_mul_f32_e32 v46, v45, v44
	v_fma_f32 v47, -v43, v46, v45
	v_fmac_f32_e32 v46, v47, v44
	v_fma_f32 v43, -v43, v46, v45
	v_div_fmas_f32 v43, v43, v44, v46
	v_div_fixup_f32 v34, v43, v42, v34
	v_mul_f32_e32 v31, v31, v34
	v_cvt_pk_bf16_f32 v30, v30, v31
	v_lshlrev_b32_e32 v31, 16, v35
	v_mul_f32_e32 v34, 0xbfb8aa3b, v31
	v_exp_f32_e32 v34, v34
	s_nop 0
	v_add_f32_e32 v34, 1.0, v34
	v_div_scale_f32 v42, s[12:13], v34, v34, v31
	v_rcp_f32_e32 v43, v42
	s_nop 0
	v_fma_f32 v44, -v42, v43, 1.0
	v_fmac_f32_e32 v43, v44, v43
	v_div_scale_f32 v44, vcc, v31, v34, v31
	v_mul_f32_e32 v45, v44, v43
	v_fma_f32 v46, -v42, v45, v44
	v_fmac_f32_e32 v45, v46, v43
	v_fma_f32 v42, -v42, v45, v44
	v_div_fmas_f32 v42, v42, v43, v45
	v_div_fixup_f32 v31, v42, v34, v31
	v_mul_f32_e32 v31, v32, v31
	v_and_b32_e32 v32, 0xffff0000, v35
	v_mul_f32_e32 v34, 0xbfb8aa3b, v32
	v_exp_f32_e32 v34, v34
	s_nop 0
	v_add_f32_e32 v34, 1.0, v34
	v_div_scale_f32 v35, s[12:13], v34, v34, v32
	v_rcp_f32_e32 v42, v35
	s_nop 0
	v_fma_f32 v43, -v35, v42, 1.0
	v_fmac_f32_e32 v42, v43, v42
	v_div_scale_f32 v43, vcc, v32, v34, v32
	v_mul_f32_e32 v44, v43, v42
	v_fma_f32 v45, -v35, v44, v43
	v_fmac_f32_e32 v44, v45, v42
	v_fma_f32 v35, -v35, v44, v43
	v_div_fmas_f32 v35, v35, v42, v44
	v_div_fixup_f32 v32, v35, v34, v32
	v_mul_f32_e32 v32, v33, v32
	v_cvt_pk_bf16_f32 v31, v31, v32
	v_lshlrev_b32_e32 v32, 16, v36
	v_mul_f32_e32 v33, 0xbfb8aa3b, v32
	v_exp_f32_e32 v33, v33
	s_nop 0
	v_add_f32_e32 v33, 1.0, v33
	v_div_scale_f32 v34, s[12:13], v33, v33, v32
	v_rcp_f32_e32 v35, v34
	s_nop 0
	v_fma_f32 v42, -v34, v35, 1.0
	v_fmac_f32_e32 v35, v42, v35
	v_div_scale_f32 v42, vcc, v32, v33, v32
	v_mul_f32_e32 v43, v42, v35
	v_fma_f32 v44, -v34, v43, v42
	v_fmac_f32_e32 v43, v44, v35
	v_fma_f32 v34, -v34, v43, v42
	v_div_fmas_f32 v34, v34, v35, v43
	v_div_fixup_f32 v32, v34, v33, v32
	v_mul_f32_e32 v26, v26, v32
	v_and_b32_e32 v32, 0xffff0000, v36
	v_mul_f32_e32 v33, 0xbfb8aa3b, v32
	v_exp_f32_e32 v33, v33
	s_nop 0
	v_add_f32_e32 v33, 1.0, v33
	v_div_scale_f32 v34, s[12:13], v33, v33, v32
	v_rcp_f32_e32 v35, v34
	s_nop 0
	v_fma_f32 v36, -v34, v35, 1.0
	v_fmac_f32_e32 v35, v36, v35
	v_div_scale_f32 v36, vcc, v32, v33, v32
	v_mul_f32_e32 v42, v36, v35
	v_fma_f32 v43, -v34, v42, v36
	v_fmac_f32_e32 v42, v43, v35
	v_fma_f32 v34, -v34, v42, v36
	v_div_fmas_f32 v34, v34, v35, v42
	v_div_fixup_f32 v32, v34, v33, v32
	v_mul_f32_e32 v27, v27, v32
	v_cvt_pk_bf16_f32 v32, v26, v27
	v_lshlrev_b32_e32 v26, 16, v37
	v_mul_f32_e32 v27, 0xbfb8aa3b, v26
	v_exp_f32_e32 v27, v27
	s_nop 0
	v_add_f32_e32 v27, 1.0, v27
	v_div_scale_f32 v33, s[12:13], v27, v27, v26
	v_rcp_f32_e32 v34, v33
	s_nop 0
	v_fma_f32 v35, -v33, v34, 1.0
	v_fmac_f32_e32 v34, v35, v34
	v_div_scale_f32 v35, vcc, v26, v27, v26
	v_mul_f32_e32 v36, v35, v34
	v_fma_f32 v42, -v33, v36, v35
	v_fmac_f32_e32 v36, v42, v34
	v_fma_f32 v33, -v33, v36, v35
	v_div_fmas_f32 v33, v33, v34, v36
	v_div_fixup_f32 v26, v33, v27, v26
	v_and_b32_e32 v27, 0xffff0000, v37
	v_mul_f32_e32 v26, v28, v26
	v_mul_f32_e32 v28, 0xbfb8aa3b, v27
	v_exp_f32_e32 v28, v28
	s_nop 0
	v_add_f32_e32 v28, 1.0, v28
	v_div_scale_f32 v33, s[12:13], v28, v28, v27
	v_rcp_f32_e32 v34, v33
	s_nop 0
	v_fma_f32 v35, -v33, v34, 1.0
	v_fmac_f32_e32 v34, v35, v34
	v_div_scale_f32 v35, vcc, v27, v28, v27
	v_mul_f32_e32 v36, v35, v34
	v_fma_f32 v37, -v33, v36, v35
	v_fmac_f32_e32 v36, v37, v34
	v_fma_f32 v33, -v33, v36, v35
	v_div_fmas_f32 v33, v33, v34, v36
	v_div_fixup_f32 v27, v33, v28, v27
	v_mul_f32_e32 v27, v29, v27
	v_cvt_pk_bf16_f32 v33, v26, v27
	v_lshl_add_u64 v[26:27], s[72:73], 0, v[38:39]
	v_lshl_add_u64 v[34:35], v[26:27], 0, v[144:145]
	global_load_dwordx4 v[26:29], v[40:41], off offset:256
	global_store_dwordx4 v[34:35], v[30:33], off
	s_waitcnt vmcnt(1)
; __device__ __forceinline__ unsigned cvt_pk_bf16(float lo, float hi) { unsigned r; asm volatile("v_cvt_pk_bf16_f32 %0, %1, %2" : "=v"(r) : "v"(lo), "v"(hi)); return r; }
; __device__ __forceinline__ float bflo(unsigned u) { return __uint_as_float(u << 16); }
; __device__ __forceinline__ float bfhi(unsigned u) { return __uint_as_float(u & 0xffff0000u); }
; __device__ __forceinline__ float silu_f(float v) { return v / (1.f + __expf(-v)); }
;     __device__ __forceinline__ void operator()(const pg8::f32x4 (&acc)[2][2][4][2], const pg8::Unit& u, int wr, int wc, int fr, int fq) const {
;     ...
;             for (int m = 0; m < 4; ++m) { const size_t row = (size_t)(row0 + ai * 128 + m * 16);
; #pragma unroll
;                 for (int bj = 0; bj < 2; ++bj) { const pg8::f32x4 v0 = acc[ai][bj][m][0], v1 = acc[ai][bj][m][1];
;                     const u32x4 gz = *(const u32x4*)(Z + row * DIN + goff + col0 + bj * 128); u32x4 w;
;                     w.x = pg8::cvt_pk_bf16(v0[0] * silu_f(bflo(gz.x)), v0[1] * silu_f(bfhi(gz.x))); w.y = pg8::cvt_pk_bf16(v0[2] * silu_f(bflo(gz.y)), v0[3] * silu_f(bfhi(gz.y)));
;                     w.z = pg8::cvt_pk_bf16(v1[0] * silu_f(bflo(gz.z)), v1[1] * silu_f(bfhi(gz.z))); w.w = pg8::cvt_pk_bf16(v1[2] * silu_f(bflo(gz.w)), v1[3] * silu_f(bfhi(gz.w)));
;                     *(u32x4*)(O + row * DM + coff + col0 + bj * 128) = w; } }
	v_lshlrev_b32_e32 v30, 16, v26
	v_mul_f32_e32 v31, 0xbfb8aa3b, v30
	v_exp_f32_e32 v31, v31
	v_and_b32_e32 v26, 0xffff0000, v26
	v_add_f32_e32 v31, 1.0, v31
	v_div_scale_f32 v32, s[12:13], v31, v31, v30
	v_rcp_f32_e32 v33, v32
	s_nop 0
	v_fma_f32 v36, -v32, v33, 1.0
	v_fmac_f32_e32 v33, v36, v33
	v_div_scale_f32 v36, vcc, v30, v31, v30
	v_mul_f32_e32 v37, v36, v33
	v_fma_f32 v38, -v32, v37, v36
	v_fmac_f32_e32 v37, v38, v33
	v_fma_f32 v32, -v32, v37, v36
	v_div_fmas_f32 v32, v32, v33, v37
	v_div_fixup_f32 v30, v32, v31, v30
	v_mul_f32_e32 v22, v22, v30
	v_mul_f32_e32 v30, 0xbfb8aa3b, v26
	v_exp_f32_e32 v30, v30
	s_nop 0
	v_add_f32_e32 v30, 1.0, v30
	v_div_scale_f32 v31, s[12:13], v30, v30, v26
	v_rcp_f32_e32 v32, v31
	s_nop 0
	v_fma_f32 v33, -v31, v32, 1.0
	v_fmac_f32_e32 v32, v33, v32
	v_div_scale_f32 v33, vcc, v26, v30, v26
	v_mul_f32_e32 v36, v33, v32
	v_fma_f32 v37, -v31, v36, v33
	v_fmac_f32_e32 v36, v37, v32
	v_fma_f32 v31, -v31, v36, v33
	v_div_fmas_f32 v31, v31, v32, v36
	v_div_fixup_f32 v26, v31, v30, v26
	v_mul_f32_e32 v23, v23, v26
	v_cvt_pk_bf16_f32 v22, v22, v23
	v_lshlrev_b32_e32 v23, 16, v27
	v_mul_f32_e32 v26, 0xbfb8aa3b, v23
	v_exp_f32_e32 v26, v26
	s_nop 0
	v_add_f32_e32 v26, 1.0, v26
	v_div_scale_f32 v30, s[12:13], v26, v26, v23
	v_rcp_f32_e32 v31, v30
	s_nop 0
	v_fma_f32 v32, -v30, v31, 1.0
	v_fmac_f32_e32 v31, v32, v31
	v_div_scale_f32 v32, vcc, v23, v26, v23
	v_mul_f32_e32 v33, v32, v31
	v_fma_f32 v36, -v30, v33, v32
	v_fmac_f32_e32 v33, v36, v31
	v_fma_f32 v30, -v30, v33, v32
	v_div_fmas_f32 v30, v30, v31, v33
	v_div_fixup_f32 v23, v30, v26, v23
	v_mul_f32_e32 v23, v24, v23
	v_and_b32_e32 v24, 0xffff0000, v27
	v_mul_f32_e32 v26, 0xbfb8aa3b, v24
	v_exp_f32_e32 v26, v26
	s_nop 0
	v_add_f32_e32 v26, 1.0, v26
	v_div_scale_f32 v27, s[12:13], v26, v26, v24
	v_rcp_f32_e32 v30, v27
	s_nop 0
	v_fma_f32 v31, -v27, v30, 1.0
	v_fmac_f32_e32 v30, v31, v30
	v_div_scale_f32 v31, vcc, v24, v26, v24
	v_mul_f32_e32 v32, v31, v30
	v_fma_f32 v33, -v27, v32, v31
	v_fmac_f32_e32 v32, v33, v30
	v_fma_f32 v27, -v27, v32, v31
	v_div_fmas_f32 v27, v27, v30, v32
	v_div_fixup_f32 v24, v27, v26, v24
	v_mul_f32_e32 v24, v25, v24
	v_cvt_pk_bf16_f32 v23, v23, v24
	v_lshlrev_b32_e32 v24, 16, v28
	v_mul_f32_e32 v25, 0xbfb8aa3b, v24
	v_exp_f32_e32 v25, v25
	s_nop 0
	v_add_f32_e32 v25, 1.0, v25
	v_div_scale_f32 v26, s[12:13], v25, v25, v24
	v_rcp_f32_e32 v27, v26
	s_nop 0
	v_fma_f32 v30, -v26, v27, 1.0
	v_fmac_f32_e32 v27, v30, v27
	v_div_scale_f32 v30, vcc, v24, v25, v24
	v_mul_f32_e32 v31, v30, v27
	v_fma_f32 v32, -v26, v31, v30
	v_fmac_f32_e32 v31, v32, v27
	v_fma_f32 v26, -v26, v31, v30
	v_div_fmas_f32 v26, v26, v27, v31
	v_div_fixup_f32 v24, v26, v25, v24
	v_mul_f32_e32 v18, v18, v24
	v_and_b32_e32 v24, 0xffff0000, v28
	v_mul_f32_e32 v25, 0xbfb8aa3b, v24
	v_exp_f32_e32 v25, v25
	s_nop 0
	v_add_f32_e32 v25, 1.0, v25
	v_div_scale_f32 v26, s[12:13], v25, v25, v24
	v_rcp_f32_e32 v27, v26
	s_nop 0
	v_fma_f32 v28, -v26, v27, 1.0
	v_fmac_f32_e32 v27, v28, v27
	v_div_scale_f32 v28, vcc, v24, v25, v24
	v_mul_f32_e32 v30, v28, v27
	v_fma_f32 v31, -v26, v30, v28
	v_fmac_f32_e32 v30, v31, v27
	v_fma_f32 v26, -v26, v30, v28
	v_div_fmas_f32 v26, v26, v27, v30
	v_div_fixup_f32 v24, v26, v25, v24
	v_mul_f32_e32 v19, v19, v24
	v_cvt_pk_bf16_f32 v24, v18, v19
	v_lshlrev_b32_e32 v18, 16, v29
	v_mul_f32_e32 v19, 0xbfb8aa3b, v18
	v_exp_f32_e32 v19, v19
	s_nop 0
	v_add_f32_e32 v19, 1.0, v19
	v_div_scale_f32 v25, s[12:13], v19, v19, v18
	v_rcp_f32_e32 v26, v25
	s_nop 0
	v_fma_f32 v27, -v25, v26, 1.0
	v_fmac_f32_e32 v26, v27, v26
	v_div_scale_f32 v27, vcc, v18, v19, v18
	v_mul_f32_e32 v28, v27, v26
	v_fma_f32 v30, -v25, v28, v27
	v_fmac_f32_e32 v28, v30, v26
	v_fma_f32 v25, -v25, v28, v27
	v_div_fmas_f32 v25, v25, v26, v28
	v_div_fixup_f32 v18, v25, v19, v18
	v_and_b32_e32 v19, 0xffff0000, v29
	v_mul_f32_e32 v18, v20, v18
	v_mul_f32_e32 v20, 0xbfb8aa3b, v19
	v_exp_f32_e32 v20, v20
	s_nop 0
	v_add_f32_e32 v20, 1.0, v20
	v_div_scale_f32 v25, s[12:13], v20, v20, v19
	v_rcp_f32_e32 v26, v25
	s_nop 0
	v_fma_f32 v27, -v25, v26, 1.0
	v_fmac_f32_e32 v26, v27, v26
	v_div_scale_f32 v27, vcc, v19, v20, v19
	v_mul_f32_e32 v28, v27, v26
	v_fma_f32 v29, -v25, v28, v27
	v_fmac_f32_e32 v28, v29, v26
	v_fma_f32 v25, -v25, v28, v27
	v_div_fmas_f32 v25, v25, v26, v28
	v_div_fixup_f32 v19, v25, v20, v19
	v_mul_f32_e32 v19, v21, v19
	v_cvt_pk_bf16_f32 v25, v18, v19
	v_add_u32_e32 v18, 0xb0, v160
	v_ashrrev_i32_e32 v19, 31, v18
	global_store_dwordx4 v[34:35], v[22:25], off offset:256
	s_nop 1
	v_lshlrev_b64 v[22:23], 12, v[18:19]
	v_mad_i64_i32 v[18:19], s[12:13], v18, s75, v[162:163]
	v_lshl_add_u64 v[18:19], v[18:19], 0, v[144:145]
	v_lshl_add_u64 v[24:25], v[18:19], 0, s[26:27]
	v_add_co_u32_e32 v18, vcc, s5, v18
	s_nop 1
	v_addc_co_u32_e32 v19, vcc, 0, v19, vcc
	global_load_dwordx4 v[18:21], v[18:19], off
	s_waitcnt vmcnt(0)
; __device__ __forceinline__ unsigned cvt_pk_bf16(float lo, float hi) { unsigned r; asm volatile("v_cvt_pk_bf16_f32 %0, %1, %2" : "=v"(r) : "v"(lo), "v"(hi)); return r; }
; __device__ __forceinline__ float bflo(unsigned u) { return __uint_as_float(u << 16); }
; __device__ __forceinline__ float bfhi(unsigned u) { return __uint_as_float(u & 0xffff0000u); }
; __device__ __forceinline__ float silu_f(float v) { return v / (1.f + __expf(-v)); }
;     __device__ __forceinline__ void operator()(const pg8::f32x4 (&acc)[2][2][4][2], const pg8::Unit& u, int wr, int wc, int fr, int fq) const {
;     ...
;             for (int m = 0; m < 4; ++m) { const size_t row = (size_t)(row0 + ai * 128 + m * 16);
; #pragma unroll
;                 for (int bj = 0; bj < 2; ++bj) { const pg8::f32x4 v0 = acc[ai][bj][m][0], v1 = acc[ai][bj][m][1];
;                     const u32x4 gz = *(const u32x4*)(Z + row * DIN + goff + col0 + bj * 128); u32x4 w;
;                     w.x = pg8::cvt_pk_bf16(v0[0] * silu_f(bflo(gz.x)), v0[1] * silu_f(bfhi(gz.x))); w.y = pg8::cvt_pk_bf16(v0[2] * silu_f(bflo(gz.y)), v0[3] * silu_f(bfhi(gz.y)));
;                     w.z = pg8::cvt_pk_bf16(v1[0] * silu_f(bflo(gz.z)), v1[1] * silu_f(bfhi(gz.z))); w.w = pg8::cvt_pk_bf16(v1[2] * silu_f(bflo(gz.w)), v1[3] * silu_f(bfhi(gz.w)));
;                     *(u32x4*)(O + row * DM + coff + col0 + bj * 128) = w; } }
	v_lshlrev_b32_e32 v26, 16, v18
	v_mul_f32_e32 v27, 0xbfb8aa3b, v26
	v_exp_f32_e32 v27, v27
	v_and_b32_e32 v18, 0xffff0000, v18
	v_add_f32_e32 v27, 1.0, v27
	v_div_scale_f32 v28, s[12:13], v27, v27, v26
	v_rcp_f32_e32 v29, v28
	s_nop 0
	v_fma_f32 v30, -v28, v29, 1.0
	v_fmac_f32_e32 v29, v30, v29
	v_div_scale_f32 v30, vcc, v26, v27, v26
	v_mul_f32_e32 v31, v30, v29
	v_fma_f32 v32, -v28, v31, v30
	v_fmac_f32_e32 v31, v32, v29
	v_fma_f32 v28, -v28, v31, v30
	v_div_fmas_f32 v28, v28, v29, v31
	v_div_fixup_f32 v26, v28, v27, v26
	v_mul_f32_e32 v14, v14, v26
	v_mul_f32_e32 v26, 0xbfb8aa3b, v18
	v_exp_f32_e32 v26, v26
	s_nop 0
	v_add_f32_e32 v26, 1.0, v26
	v_div_scale_f32 v27, s[12:13], v26, v26, v18
	v_rcp_f32_e32 v28, v27
	s_nop 0
	v_fma_f32 v29, -v27, v28, 1.0
	v_fmac_f32_e32 v28, v29, v28
	v_div_scale_f32 v29, vcc, v18, v26, v18
	v_mul_f32_e32 v30, v29, v28
	v_fma_f32 v31, -v27, v30, v29
	v_fmac_f32_e32 v30, v31, v28
	v_fma_f32 v27, -v27, v30, v29
	v_div_fmas_f32 v27, v27, v28, v30
	v_div_fixup_f32 v18, v27, v26, v18
	v_mul_f32_e32 v15, v15, v18
	v_cvt_pk_bf16_f32 v14, v14, v15
	v_lshlrev_b32_e32 v15, 16, v19
	v_mul_f32_e32 v18, 0xbfb8aa3b, v15
	v_exp_f32_e32 v18, v18
	s_nop 0
	v_add_f32_e32 v18, 1.0, v18
	v_div_scale_f32 v26, s[12:13], v18, v18, v15
	v_rcp_f32_e32 v27, v26
	s_nop 0
	v_fma_f32 v28, -v26, v27, 1.0
	v_fmac_f32_e32 v27, v28, v27
	v_div_scale_f32 v28, vcc, v15, v18, v15
	v_mul_f32_e32 v29, v28, v27
	v_fma_f32 v30, -v26, v29, v28
	v_fmac_f32_e32 v29, v30, v27
	v_fma_f32 v26, -v26, v29, v28
	v_div_fmas_f32 v26, v26, v27, v29
	v_div_fixup_f32 v15, v26, v18, v15
	v_mul_f32_e32 v15, v16, v15
	v_and_b32_e32 v16, 0xffff0000, v19
	v_mul_f32_e32 v18, 0xbfb8aa3b, v16
	v_exp_f32_e32 v18, v18
	s_nop 0
	v_add_f32_e32 v18, 1.0, v18
	v_div_scale_f32 v19, s[12:13], v18, v18, v16
	v_rcp_f32_e32 v26, v19
	s_nop 0
	v_fma_f32 v27, -v19, v26, 1.0
	v_fmac_f32_e32 v26, v27, v26
	v_div_scale_f32 v27, vcc, v16, v18, v16
	v_mul_f32_e32 v28, v27, v26
	v_fma_f32 v29, -v19, v28, v27
	v_fmac_f32_e32 v28, v29, v26
	v_fma_f32 v19, -v19, v28, v27
	v_div_fmas_f32 v19, v19, v26, v28
	v_div_fixup_f32 v16, v19, v18, v16
	v_mul_f32_e32 v16, v17, v16
	v_cvt_pk_bf16_f32 v15, v15, v16
	v_lshlrev_b32_e32 v16, 16, v20
	v_mul_f32_e32 v17, 0xbfb8aa3b, v16
	v_exp_f32_e32 v17, v17
	s_nop 0
	v_add_f32_e32 v17, 1.0, v17
	v_div_scale_f32 v18, s[12:13], v17, v17, v16
	v_rcp_f32_e32 v19, v18
	s_nop 0
	v_fma_f32 v26, -v18, v19, 1.0
	v_fmac_f32_e32 v19, v26, v19
	v_div_scale_f32 v26, vcc, v16, v17, v16
	v_mul_f32_e32 v27, v26, v19
	v_fma_f32 v28, -v18, v27, v26
	v_fmac_f32_e32 v27, v28, v19
	v_fma_f32 v18, -v18, v27, v26
	v_div_fmas_f32 v18, v18, v19, v27
	v_div_fixup_f32 v16, v18, v17, v16
	v_mul_f32_e32 v10, v10, v16
	v_and_b32_e32 v16, 0xffff0000, v20
	v_mul_f32_e32 v17, 0xbfb8aa3b, v16
	v_exp_f32_e32 v17, v17
	s_nop 0
	v_add_f32_e32 v17, 1.0, v17
	v_div_scale_f32 v18, s[12:13], v17, v17, v16
	v_rcp_f32_e32 v19, v18
	s_nop 0
	v_fma_f32 v20, -v18, v19, 1.0
	v_fmac_f32_e32 v19, v20, v19
	v_div_scale_f32 v20, vcc, v16, v17, v16
	v_mul_f32_e32 v26, v20, v19
	v_fma_f32 v27, -v18, v26, v20
	v_fmac_f32_e32 v26, v27, v19
	v_fma_f32 v18, -v18, v26, v20
	v_div_fmas_f32 v18, v18, v19, v26
	v_div_fixup_f32 v16, v18, v17, v16
	v_mul_f32_e32 v11, v11, v16
	v_cvt_pk_bf16_f32 v16, v10, v11
	v_lshlrev_b32_e32 v10, 16, v21
	v_mul_f32_e32 v11, 0xbfb8aa3b, v10
	v_exp_f32_e32 v11, v11
	s_nop 0
	v_add_f32_e32 v11, 1.0, v11
	v_div_scale_f32 v17, s[12:13], v11, v11, v10
	v_rcp_f32_e32 v18, v17
	s_nop 0
	v_fma_f32 v19, -v17, v18, 1.0
	v_fmac_f32_e32 v18, v19, v18
	v_div_scale_f32 v19, vcc, v10, v11, v10
	v_mul_f32_e32 v20, v19, v18
	v_fma_f32 v26, -v17, v20, v19
	v_fmac_f32_e32 v20, v26, v18
	v_fma_f32 v17, -v17, v20, v19
	v_div_fmas_f32 v17, v17, v18, v20
	v_div_fixup_f32 v10, v17, v11, v10
	v_and_b32_e32 v11, 0xffff0000, v21
	v_mul_f32_e32 v10, v12, v10
	v_mul_f32_e32 v12, 0xbfb8aa3b, v11
	v_exp_f32_e32 v12, v12
	s_nop 0
	v_add_f32_e32 v12, 1.0, v12
	v_div_scale_f32 v17, s[12:13], v12, v12, v11
	v_rcp_f32_e32 v18, v17
	s_nop 0
	v_fma_f32 v19, -v17, v18, 1.0
	v_fmac_f32_e32 v18, v19, v18
	v_div_scale_f32 v19, vcc, v11, v12, v11
	v_mul_f32_e32 v20, v19, v18
	v_fma_f32 v21, -v17, v20, v19
	v_fmac_f32_e32 v20, v21, v18
	v_fma_f32 v17, -v17, v20, v19
	v_div_fmas_f32 v17, v17, v18, v20
	v_div_fixup_f32 v11, v17, v12, v11
	v_mul_f32_e32 v11, v13, v11
	v_cvt_pk_bf16_f32 v17, v10, v11
	v_lshl_add_u64 v[10:11], s[72:73], 0, v[22:23]
	v_lshl_add_u64 v[18:19], v[10:11], 0, v[144:145]
	global_load_dwordx4 v[10:13], v[24:25], off offset:256
	global_store_dwordx4 v[18:19], v[14:17], off
	s_waitcnt vmcnt(1)
; __device__ __forceinline__ unsigned cvt_pk_bf16(float lo, float hi) { unsigned r; asm volatile("v_cvt_pk_bf16_f32 %0, %1, %2" : "=v"(r) : "v"(lo), "v"(hi)); return r; }
; #define PG8_BAR __builtin_amdgcn_s_barrier()
; __device__ __forceinline__ float bflo(unsigned u) { return __uint_as_float(u << 16); }
; __device__ __forceinline__ float bfhi(unsigned u) { return __uint_as_float(u & 0xffff0000u); }
; __device__ __forceinline__ float silu_f(float v) { return v / (1.f + __expf(-v)); }
; template <class Epi, class Sched, bool ALIGN_EPI>
; __device__ __forceinline__ void gemm_phase(PG8_LAS unsigned char* lds, const Gemm g, const Sched& S, const Epi& E) {
;     ...
;         if (!has_next) break;
; #pragma unroll
;         for (int a = 0; a < 2; ++a)
; #pragma unroll
;             for (int b = 0; b < 2; ++b)
; #pragma unroll
;                 for (int m = 0; m < 4; ++m)
; #pragma unroll
;                     for (int n = 0; n < 2; ++n) acc[a][b][m][n] = (f32x4){0.f, 0.f, 0.f, 0.f};
;         cur = nxt; cA = nA; cB = nB; ++ui;
;         if constexpr (ALIGN_EPI) { if (wr == 1) PG8_BAR; }
;     __device__ __forceinline__ void operator()(const pg8::f32x4 (&acc)[2][2][4][2], const pg8::Unit& u, int wr, int wc, int fr, int fq) const {
;     ...
;             for (int m = 0; m < 4; ++m) { const size_t row = (size_t)(row0 + ai * 128 + m * 16);
; #pragma unroll
;                 for (int bj = 0; bj < 2; ++bj) { const pg8::f32x4 v0 = acc[ai][bj][m][0], v1 = acc[ai][bj][m][1];
;                     const u32x4 gz = *(const u32x4*)(Z + row * DIN + goff + col0 + bj * 128); u32x4 w;
;                     w.x = pg8::cvt_pk_bf16(v0[0] * silu_f(bflo(gz.x)), v0[1] * silu_f(bfhi(gz.x))); w.y = pg8::cvt_pk_bf16(v0[2] * silu_f(bflo(gz.y)), v0[3] * silu_f(bfhi(gz.y)));
;                     w.z = pg8::cvt_pk_bf16(v1[0] * silu_f(bflo(gz.z)), v1[1] * silu_f(bfhi(gz.z))); w.w = pg8::cvt_pk_bf16(v1[2] * silu_f(bflo(gz.w)), v1[3] * silu_f(bfhi(gz.w)));
;                     *(u32x4*)(O + row * DM + coff + col0 + bj * 128) = w; } }
	v_lshlrev_b32_e32 v14, 16, v10
	v_mul_f32_e32 v15, 0xbfb8aa3b, v14
	v_exp_f32_e32 v15, v15
	v_and_b32_e32 v10, 0xffff0000, v10
	v_add_f32_e32 v15, 1.0, v15
	v_div_scale_f32 v16, s[12:13], v15, v15, v14
	v_rcp_f32_e32 v17, v16
	s_nop 0
	v_fma_f32 v20, -v16, v17, 1.0
	v_fmac_f32_e32 v17, v20, v17
	v_div_scale_f32 v20, vcc, v14, v15, v14
	v_mul_f32_e32 v21, v20, v17
	v_fma_f32 v22, -v16, v21, v20
	v_fmac_f32_e32 v21, v22, v17
	v_fma_f32 v16, -v16, v21, v20
	v_div_fmas_f32 v16, v16, v17, v21
	v_div_fixup_f32 v14, v16, v15, v14
	v_mul_f32_e32 v6, v6, v14
	v_mul_f32_e32 v14, 0xbfb8aa3b, v10
	v_exp_f32_e32 v14, v14
	s_nop 0
	v_add_f32_e32 v14, 1.0, v14
	v_div_scale_f32 v15, s[12:13], v14, v14, v10
	v_rcp_f32_e32 v16, v15
	s_nop 0
	v_fma_f32 v17, -v15, v16, 1.0
	v_fmac_f32_e32 v16, v17, v16
	v_div_scale_f32 v17, vcc, v10, v14, v10
	v_mul_f32_e32 v20, v17, v16
	v_fma_f32 v21, -v15, v20, v17
	v_fmac_f32_e32 v20, v21, v16
	v_fma_f32 v15, -v15, v20, v17
	v_div_fmas_f32 v15, v15, v16, v20
	v_div_fixup_f32 v10, v15, v14, v10
	v_mul_f32_e32 v7, v7, v10
	v_cvt_pk_bf16_f32 v6, v6, v7
	v_lshlrev_b32_e32 v7, 16, v11
	v_mul_f32_e32 v10, 0xbfb8aa3b, v7
	v_exp_f32_e32 v10, v10
	s_nop 0
	v_add_f32_e32 v10, 1.0, v10
	v_div_scale_f32 v14, s[12:13], v10, v10, v7
	v_rcp_f32_e32 v15, v14
	s_nop 0
	v_fma_f32 v16, -v14, v15, 1.0
	v_fmac_f32_e32 v15, v16, v15
	v_div_scale_f32 v16, vcc, v7, v10, v7
	v_mul_f32_e32 v17, v16, v15
	v_fma_f32 v20, -v14, v17, v16
	v_fmac_f32_e32 v17, v20, v15
	v_fma_f32 v14, -v14, v17, v16
	v_div_fmas_f32 v14, v14, v15, v17
	v_div_fixup_f32 v7, v14, v10, v7
	v_mul_f32_e32 v7, v8, v7
	v_and_b32_e32 v8, 0xffff0000, v11
	v_mul_f32_e32 v10, 0xbfb8aa3b, v8
	v_exp_f32_e32 v10, v10
	s_nop 0
	v_add_f32_e32 v10, 1.0, v10
	v_div_scale_f32 v11, s[12:13], v10, v10, v8
	v_rcp_f32_e32 v14, v11
	s_nop 0
	v_fma_f32 v15, -v11, v14, 1.0
	v_fmac_f32_e32 v14, v15, v14
	v_div_scale_f32 v15, vcc, v8, v10, v8
	v_mul_f32_e32 v16, v15, v14
	v_fma_f32 v17, -v11, v16, v15
	v_fmac_f32_e32 v16, v17, v14
	v_fma_f32 v11, -v11, v16, v15
	v_div_fmas_f32 v11, v11, v14, v16
	v_div_fixup_f32 v8, v11, v10, v8
	v_mul_f32_e32 v8, v9, v8
	v_cvt_pk_bf16_f32 v7, v7, v8
	v_lshlrev_b32_e32 v8, 16, v12
	v_mul_f32_e32 v9, 0xbfb8aa3b, v8
	v_exp_f32_e32 v9, v9
	s_nop 0
	v_add_f32_e32 v9, 1.0, v9
	v_div_scale_f32 v10, s[12:13], v9, v9, v8
	v_rcp_f32_e32 v11, v10
	s_nop 0
	v_fma_f32 v14, -v10, v11, 1.0
	v_fmac_f32_e32 v11, v14, v11
	v_div_scale_f32 v14, vcc, v8, v9, v8
	v_mul_f32_e32 v15, v14, v11
	v_fma_f32 v16, -v10, v15, v14
	v_fmac_f32_e32 v15, v16, v11
	v_fma_f32 v10, -v10, v15, v14
	v_div_fmas_f32 v10, v10, v11, v15
	v_div_fixup_f32 v8, v10, v9, v8
	v_mul_f32_e32 v2, v2, v8
	v_and_b32_e32 v8, 0xffff0000, v12
	v_mul_f32_e32 v9, 0xbfb8aa3b, v8
	v_exp_f32_e32 v9, v9
	s_nop 0
	v_add_f32_e32 v9, 1.0, v9
	v_div_scale_f32 v10, s[12:13], v9, v9, v8
	v_rcp_f32_e32 v11, v10
	s_nop 0
	v_fma_f32 v12, -v10, v11, 1.0
	v_fmac_f32_e32 v11, v12, v11
	v_div_scale_f32 v12, vcc, v8, v9, v8
	v_mul_f32_e32 v14, v12, v11
	v_fma_f32 v15, -v10, v14, v12
	v_fmac_f32_e32 v14, v15, v11
	v_fma_f32 v10, -v10, v14, v12
	v_div_fmas_f32 v10, v10, v11, v14
	v_div_fixup_f32 v8, v10, v9, v8
	v_mul_f32_e32 v3, v3, v8
	v_cvt_pk_bf16_f32 v8, v2, v3
	v_lshlrev_b32_e32 v2, 16, v13
	v_mul_f32_e32 v3, 0xbfb8aa3b, v2
	v_exp_f32_e32 v3, v3
	s_nop 0
	v_add_f32_e32 v3, 1.0, v3
	v_div_scale_f32 v9, s[12:13], v3, v3, v2
	v_rcp_f32_e32 v10, v9
	s_nop 0
	v_fma_f32 v11, -v9, v10, 1.0
	v_fmac_f32_e32 v10, v11, v10
	v_div_scale_f32 v11, vcc, v2, v3, v2
	v_mul_f32_e32 v12, v11, v10
	v_fma_f32 v14, -v9, v12, v11
	v_fmac_f32_e32 v12, v14, v10
	v_fma_f32 v9, -v9, v12, v11
	v_div_fmas_f32 v9, v9, v10, v12
	v_div_fixup_f32 v2, v9, v3, v2
	v_and_b32_e32 v3, 0xffff0000, v13
	v_mul_f32_e32 v2, v4, v2
	v_mul_f32_e32 v4, 0xbfb8aa3b, v3
	v_exp_f32_e32 v4, v4
	s_nop 0
	v_add_f32_e32 v4, 1.0, v4
	v_div_scale_f32 v9, s[12:13], v4, v4, v3
	v_rcp_f32_e32 v10, v9
	s_nop 0
	v_fma_f32 v11, -v9, v10, 1.0
	v_fmac_f32_e32 v10, v11, v10
	v_div_scale_f32 v11, vcc, v3, v4, v3
	v_mul_f32_e32 v12, v11, v10
	v_fma_f32 v13, -v9, v12, v11
	v_fmac_f32_e32 v12, v13, v10
	v_fma_f32 v9, -v9, v12, v11
	v_div_fmas_f32 v9, v9, v10, v12
	v_div_fixup_f32 v3, v9, v4, v3
	s_andn2_b64 vcc, exec, s[40:41]
	v_mul_f32_e32 v3, v5, v3
	v_cvt_pk_bf16_f32 v9, v2, v3
	global_store_dwordx4 v[18:19], v[6:9], off offset:256
	s_cbranch_vccnz .LBB0_544
	s_andn2_b64 vcc, exec, s[36:37]
	s_cbranch_vccnz .LBB0_543
	s_barrier
	s_branch .LBB0_543
